# v014 + GEMM K-loops: first iteration peeled with C=0 MFMAs instead of zeroing 128 accumulator registers per tile
# baseline (speedup 1.0000x reference)
;     DI bool next(int i, Unit& u) const { if (i > 0 || c >= 64) return false; u.pm = c & 31; u.pn = 0; u.src = c >> 5; return true; }
; #define PG8_STAGE(bufoff, gbase, voff) do { _Pragma("unroll") for (int _i = 0; _i < 2; ++_i) \
;         __builtin_amdgcn_global_load_lds((const unsigned*)((const char*)(gbase) + (voff)[_i]), (LAS unsigned*)(lds + (bufoff) + ldsw + _i * 8192), 16, 0, 0); } while (0)
; #define PG8_LDA(dst, b, h) do { _Pragma("unroll") for (int m = 0; m < 4; ++m) _Pragma("unroll") for (int k = 0; k < 2; ++k) dst[m][k] = *(const LAS bf16x8*)(lds + PG8_SA(b, h) + aoff + m * 2048 + k * 1024); } while (0)
; #define PG8_LDB(dst, b, h) do { _Pragma("unroll") for (int n = 0; n < 2; ++n) _Pragma("unroll") for (int k = 0; k < 2; ++k) dst[n][k] = *(const LAS bf16x8*)(lds + PG8_SB(b, h) + boff + n * 2048 + k * 1024); } while (0)
; #define PG8_WAIT_V(n) asm volatile("s_waitcnt vmcnt(" #n ")" ::: "memory")
; #define PG8_WAIT_L(n) asm volatile("s_waitcnt lgkmcnt(" #n ")" ::: "memory")
; #define PG8_BAR __builtin_amdgcn_s_barrier()
; #define PG8_SCHED __builtin_amdgcn_sched_barrier(0)
; template <class Epi, class Sched>
; DI void gemm_phase(LAS unsigned char* lds, const Gemm g, const Sched& S, const Epi& E) {
;     ...
;         const bool has_next = S.next(ui + 1, nxt);
;         E.pre(pre, cur, wr, fr);
;         const char* nA = has_next ? (const char*)(nxt.src ? g.A1 : g.A0) + (size_t)nxt.pm * tstepA : cA; const char* nB = has_next ? (const char*)(nxt.src ? g.B1 : g.B0) + (size_t)nxt.pn * tstepB : cB;
;         for (int t = 0; t < nt; t += 2) {
;             const bool last = (t == nt - 2);
;             const char* a1 = cA + (size_t)(t + 1) * kstep;
;             const char* a2 = last ? nA : cA + (size_t)(t + 2) * kstep; const char* b2 = last ? nB : cB + (size_t)(t + 2) * kstep;
;             const char* a3 = a2 + kstep; const char* b3 = b2 + kstep;
;             PG8_LDB(B0, 0, 0); PG8_LDB(B1, 0, 1); PG8_SCHED; PG8_LDA(At, 0, 0); PG8_STAGE(PG8_SA(1, 1), a1 + hstepA, voffA);
;             PG8_WAIT_V(8); PG8_WAIT_L(0); PG8_BAR; PG8_MMA(0, 0, At, B0); PG8_MMA(0, 1, At, B1); PG8_BAR; PG8_SCHED;
;             PG8_LDA(At, 0, 1); PG8_STAGE(PG8_SB(0, 0), b2, voffB); PG8_STAGE(PG8_SB(0, 1), b2 + hstepB, voffB); PG8_STAGE(PG8_SA(0, 0), a2, voffA);
;             PG8_WAIT_V(8); PG8_WAIT_L(0); PG8_BAR; PG8_MMA(1, 0, At, B0); PG8_MMA(1, 1, At, B1); PG8_BAR; PG8_SCHED;
.LBB0_178:
	v_lshl_add_u32 v156, s44, 8, v147
	v_ashrrev_i32_e32 v157, 31, v156
	v_add_u32_e32 v154, 0x80, v156
	v_add_u32_e32 v152, 0x90, v156
	v_add_u32_e32 v150, 0xa0, v156
	v_add_u32_e32 v148, 0xb0, v156
	v_lshl_add_u64 v[2:3], v[156:157], 2, s[12:13]
	v_ashrrev_i32_e32 v155, 31, v154
	v_ashrrev_i32_e32 v153, 31, v152
	v_ashrrev_i32_e32 v151, 31, v150
	v_ashrrev_i32_e32 v149, 31, v148
	v_lshl_add_u64 v[4:5], v[154:155], 2, s[12:13]
	v_lshl_add_u64 v[6:7], v[152:153], 2, s[12:13]
	v_lshl_add_u64 v[8:9], v[150:151], 2, s[12:13]
	v_lshl_add_u64 v[10:11], v[148:149], 2, s[12:13]
	global_load_dword v166, v[2:3], off
	global_load_dword v165, v[2:3], off offset:64
	global_load_dword v164, v[2:3], off offset:128
	global_load_dword v157, v[2:3], off offset:192
	global_load_dword v155, v[4:5], off
	global_load_dword v153, v[6:7], off
	global_load_dword v151, v[8:9], off
	global_load_dword v149, v[10:11], off
	s_ashr_i32 s35, s34, 31
	s_lshl_b64 s[36:37], s[34:35], 19
	s_add_u32 s36, s30, s36
	s_addc_u32 s37, s31, s37
	s_and_b64 s[38:39], s[4:5], exec
	s_cselect_b32 s35, s37, s41
	s_cselect_b32 s61, s36, s40
	s_ashr_i32 s21, s20, 31
	s_lshl_b64 s[38:39], s[20:21], 19
	s_add_u32 s38, s28, s38
	s_addc_u32 s39, s29, s39
	s_and_b64 s[44:45], s[4:5], exec
	s_cselect_b32 s21, s39, s43
	s_cselect_b32 s62, s38, s42
	s_add_u32 s40, s40, 0x40080
	s_addc_u32 s41, s41, 0
	s_add_u32 s63, s42, 0x100
	s_addc_u32 s64, s43, 0
	s_mov_b32 s65, -2
	ds_read_b128 v[168:171], v162
	ds_read_b128 v[172:175], v162 offset:1024
	ds_read_b128 v[176:179], v162 offset:2048
	ds_read_b128 v[180:183], v162 offset:3072
	ds_read_b128 v[186:189], v163
	ds_read_b128 v[190:193], v163 offset:1024
	ds_read_b128 v[194:197], v163 offset:2048
	ds_read_b128 v[198:201], v163 offset:3072
	s_add_u32 s42, s40, 0xfffc0080
	s_addc_u32 s43, s41, -1
	s_cmp_eq_u32 s65, 12
	s_cselect_b32 s45, s35, s43
	s_cselect_b32 s44, s61, s42
	s_cselect_b32 s43, s21, s64
	s_cselect_b32 s42, s62, s63
	v_lshl_add_u64 v[234:235], s[40:41], 0, v[138:139]
	s_add_i32 m0, s49, 0xc000
	ds_read_b128 v[202:205], v160
	ds_read_b128 v[206:209], v160 offset:1024
	ds_read_b128 v[210:213], v160 offset:2048
	ds_read_b128 v[214:217], v160 offset:3072
	ds_read_b128 v[218:221], v160 offset:4096
	ds_read_b128 v[222:225], v160 offset:5120
	ds_read_b128 v[226:229], v160 offset:6144
	ds_read_b128 v[230:233], v160 offset:7168
	global_load_lds_dwordx4 v[234:235], off
	v_lshl_add_u64 v[234:235], s[40:41], 0, v[140:141]
	s_add_i32 m0, s49, 0xe000
	s_nop 0
	global_load_lds_dwordx4 v[234:235], off
	s_waitcnt vmcnt(8)
	s_waitcnt lgkmcnt(0)
	s_barrier
	s_setprio 1
	s_waitcnt lgkmcnt(0)
	v_mfma_f32_16x16x32_bf16 v[126:129], v[168:171], v[202:205], 0
	v_mfma_f32_16x16x32_bf16 v[118:121], v[176:179], v[202:205], 0
	v_mfma_f32_16x16x32_bf16 v[110:113], v[168:171], v[210:213], 0
	v_mfma_f32_16x16x32_bf16 v[102:105], v[176:179], v[210:213], 0
	v_mfma_f32_16x16x32_bf16 v[94:97], v[168:171], v[218:221], 0
	v_mfma_f32_16x16x32_bf16 v[86:89], v[176:179], v[218:221], 0
	v_mfma_f32_16x16x32_bf16 v[78:81], v[168:171], v[226:229], 0
	v_mfma_f32_16x16x32_bf16 v[70:73], v[176:179], v[226:229], 0
	v_mfma_f32_16x16x32_bf16 v[126:129], v[172:175], v[206:209], v[126:129]
	v_mfma_f32_16x16x32_bf16 v[118:121], v[180:183], v[206:209], v[118:121]
	v_mfma_f32_16x16x32_bf16 v[110:113], v[172:175], v[214:217], v[110:113]
	v_mfma_f32_16x16x32_bf16 v[102:105], v[180:183], v[214:217], v[102:105]
	v_mfma_f32_16x16x32_bf16 v[94:97], v[172:175], v[222:225], v[94:97]
	v_mfma_f32_16x16x32_bf16 v[86:89], v[180:183], v[222:225], v[86:89]
	v_mfma_f32_16x16x32_bf16 v[78:81], v[172:175], v[230:233], v[78:81]
	v_mfma_f32_16x16x32_bf16 v[70:73], v[180:183], v[230:233], v[70:73]
	s_setprio 0
	s_setprio 1
	v_mfma_f32_16x16x32_bf16 v[122:125], v[186:189], v[202:205], 0
	v_mfma_f32_16x16x32_bf16 v[114:117], v[194:197], v[202:205], 0
	v_mfma_f32_16x16x32_bf16 v[106:109], v[186:189], v[210:213], 0
	v_mfma_f32_16x16x32_bf16 v[98:101], v[194:197], v[210:213], 0
	v_mfma_f32_16x16x32_bf16 v[90:93], v[186:189], v[218:221], 0
	v_mfma_f32_16x16x32_bf16 v[82:85], v[194:197], v[218:221], 0
	v_mfma_f32_16x16x32_bf16 v[74:77], v[186:189], v[226:229], 0
	v_mfma_f32_16x16x32_bf16 v[66:69], v[194:197], v[226:229], 0
	v_mfma_f32_16x16x32_bf16 v[122:125], v[190:193], v[206:209], v[122:125]
	v_mfma_f32_16x16x32_bf16 v[114:117], v[198:201], v[206:209], v[114:117]
	v_mfma_f32_16x16x32_bf16 v[106:109], v[190:193], v[214:217], v[106:109]
	v_mfma_f32_16x16x32_bf16 v[98:101], v[198:201], v[214:217], v[98:101]
	v_mfma_f32_16x16x32_bf16 v[90:93], v[190:193], v[222:225], v[90:93]
	v_mfma_f32_16x16x32_bf16 v[82:85], v[198:201], v[222:225], v[82:85]
	v_mfma_f32_16x16x32_bf16 v[74:77], v[190:193], v[230:233], v[74:77]
	v_mfma_f32_16x16x32_bf16 v[66:69], v[198:201], v[230:233], v[66:69]
	s_setprio 0
	s_barrier
	s_add_i32 s66, s57, s46
	v_lshl_add_u64 v[234:235], s[42:43], 0, v[134:135]
	s_mov_b32 m0, s66
	ds_read_b128 v[202:205], v160 offset:16384
	ds_read_b128 v[206:209], v160 offset:17408
	ds_read_b128 v[210:213], v160 offset:18432
	ds_read_b128 v[214:217], v160 offset:19456
	ds_read_b128 v[218:221], v160 offset:20480
	ds_read_b128 v[222:225], v160 offset:21504
	ds_read_b128 v[226:229], v160 offset:22528
	ds_read_b128 v[230:233], v160 offset:23552
	global_load_lds_dwordx4 v[234:235], off
	s_add_i32 m0, s66, 0x2000
	s_add_u32 s66, s42, 0x40000
	v_lshl_add_u64 v[236:237], s[42:43], 0, v[130:131]
	s_addc_u32 s67, s43, 0
	s_add_i32 s68, s58, s46
	global_load_lds_dwordx4 v[236:237], off
	v_lshl_add_u64 v[238:239], s[66:67], 0, v[134:135]
	s_mov_b32 m0, s68
	v_lshl_add_u64 v[240:241], s[44:45], 0, v[132:133]
	global_load_lds_dwordx4 v[238:239], off
	v_lshl_add_u64 v[238:239], s[66:67], 0, v[130:131]
	s_add_i32 m0, s68, 0x2000
	s_nop 0
	global_load_lds_dwordx4 v[238:239], off
	v_lshl_add_u64 v[238:239], s[44:45], 0, v[136:137]
	s_mov_b32 m0, s49
	s_nop 0
	global_load_lds_dwordx4 v[238:239], off
	s_mov_b32 m0, s50
	s_nop 0
	global_load_lds_dwordx4 v[240:241], off
	s_waitcnt vmcnt(8)
	s_waitcnt lgkmcnt(0)
	s_barrier
; #define PG8_STAGE(bufoff, gbase, voff) do { _Pragma("unroll") for (int _i = 0; _i < 2; ++_i) \
;         __builtin_amdgcn_global_load_lds((const unsigned*)((const char*)(gbase) + (voff)[_i]), (LAS unsigned*)(lds + (bufoff) + ldsw + _i * 8192), 16, 0, 0); } while (0)
; #define PG8_LDA(dst, b, h) do { _Pragma("unroll") for (int m = 0; m < 4; ++m) _Pragma("unroll") for (int k = 0; k < 2; ++k) dst[m][k] = *(const LAS bf16x8*)(lds + PG8_SA(b, h) + aoff + m * 2048 + k * 1024); } while (0)
; #define PG8_LDB(dst, b, h) do { _Pragma("unroll") for (int n = 0; n < 2; ++n) _Pragma("unroll") for (int k = 0; k < 2; ++k) dst[n][k] = *(const LAS bf16x8*)(lds + PG8_SB(b, h) + boff + n * 2048 + k * 1024); } while (0)
; #define PG8_MMA(ai, bj, At, Bt) do { __builtin_amdgcn_s_setprio(1); _Pragma("unroll") for (int m = 0; m < 4; ++m) _Pragma("unroll") for (int n = 0; n < 2; ++n) _Pragma("unroll") for (int k = 0; k < 2; ++k) \
;         acc[ai][bj][m][n] = __builtin_amdgcn_mfma_f32_16x16x32_bf16(Bt[n][k], At[m][k], acc[ai][bj][m][n], 0, 0, 0); __builtin_amdgcn_s_setprio(0); } while (0)
; #define PG8_WAIT_V(n) asm volatile("s_waitcnt vmcnt(" #n ")" ::: "memory")
; #define PG8_WAIT_L(n) asm volatile("s_waitcnt lgkmcnt(" #n ")" ::: "memory")
; #define PG8_BAR __builtin_amdgcn_s_barrier()
; #define PG8_SCHED __builtin_amdgcn_sched_barrier(0)
; template <class Epi, class Sched>
; DI void gemm_phase(LAS unsigned char* lds, const Gemm g, const Sched& S, const Epi& E) {
;     ...
;             PG8_WAIT_V(8); PG8_WAIT_L(0); PG8_BAR; PG8_MMA(1, 0, At, B0); PG8_MMA(1, 1, At, B1); PG8_BAR; PG8_SCHED;
;             PG8_LDB(B0, 1, 0); PG8_LDB(B1, 1, 1); PG8_SCHED; PG8_LDA(At, 1, 0); PG8_STAGE(PG8_SA(0, 1), a2 + hstepA, voffA);
;             PG8_WAIT_V(8); PG8_WAIT_L(0); PG8_BAR; PG8_MMA(0, 0, At, B0); PG8_MMA(0, 1, At, B1); PG8_BAR; PG8_SCHED;
	s_setprio 1
	s_waitcnt lgkmcnt(0)
	v_mfma_f32_16x16x32_bf16 v[62:65], v[168:171], v[202:205], 0
	v_mfma_f32_16x16x32_bf16 v[54:57], v[176:179], v[202:205], 0
	v_mfma_f32_16x16x32_bf16 v[46:49], v[168:171], v[210:213], 0
	v_mfma_f32_16x16x32_bf16 v[38:41], v[176:179], v[210:213], 0
	v_mfma_f32_16x16x32_bf16 v[30:33], v[168:171], v[218:221], 0
	v_mfma_f32_16x16x32_bf16 v[22:25], v[176:179], v[218:221], 0
	v_mfma_f32_16x16x32_bf16 v[14:17], v[168:171], v[226:229], 0
	v_mfma_f32_16x16x32_bf16 v[6:9], v[176:179], v[226:229], 0
	v_mfma_f32_16x16x32_bf16 v[62:65], v[172:175], v[206:209], v[62:65]
	v_mfma_f32_16x16x32_bf16 v[54:57], v[180:183], v[206:209], v[54:57]
	v_mfma_f32_16x16x32_bf16 v[46:49], v[172:175], v[214:217], v[46:49]
	v_mfma_f32_16x16x32_bf16 v[38:41], v[180:183], v[214:217], v[38:41]
	v_mfma_f32_16x16x32_bf16 v[30:33], v[172:175], v[222:225], v[30:33]
	v_mfma_f32_16x16x32_bf16 v[22:25], v[180:183], v[222:225], v[22:25]
	v_mfma_f32_16x16x32_bf16 v[14:17], v[172:175], v[230:233], v[14:17]
	v_mfma_f32_16x16x32_bf16 v[6:9], v[180:183], v[230:233], v[6:9]
	s_setprio 0
	s_setprio 1
	v_mfma_f32_16x16x32_bf16 v[58:61], v[186:189], v[202:205], 0
	v_mfma_f32_16x16x32_bf16 v[50:53], v[194:197], v[202:205], 0
	v_mfma_f32_16x16x32_bf16 v[42:45], v[186:189], v[210:213], 0
	v_mfma_f32_16x16x32_bf16 v[34:37], v[194:197], v[210:213], 0
	v_mfma_f32_16x16x32_bf16 v[26:29], v[186:189], v[218:221], 0
	v_mfma_f32_16x16x32_bf16 v[18:21], v[194:197], v[218:221], 0
	v_mfma_f32_16x16x32_bf16 v[10:13], v[186:189], v[226:229], 0
	v_mfma_f32_16x16x32_bf16 v[2:5], v[194:197], v[226:229], 0
	v_mfma_f32_16x16x32_bf16 v[58:61], v[190:193], v[206:209], v[58:61]
	v_mfma_f32_16x16x32_bf16 v[50:53], v[198:201], v[206:209], v[50:53]
	v_mfma_f32_16x16x32_bf16 v[42:45], v[190:193], v[214:217], v[42:45]
	v_mfma_f32_16x16x32_bf16 v[34:37], v[198:201], v[214:217], v[34:37]
	v_mfma_f32_16x16x32_bf16 v[26:29], v[190:193], v[222:225], v[26:29]
	v_mfma_f32_16x16x32_bf16 v[18:21], v[198:201], v[222:225], v[18:21]
	v_mfma_f32_16x16x32_bf16 v[10:13], v[190:193], v[230:233], v[10:13]
	v_mfma_f32_16x16x32_bf16 v[2:5], v[198:201], v[230:233], v[2:5]
	s_setprio 0
	s_barrier
	s_add_i32 s66, 0, 0x18000
	v_add_u32_e32 v167, s66, v158
	s_add_i32 s67, 0, 0x1c000
	ds_read_b128 v[168:171], v167
	ds_read_b128 v[172:175], v167 offset:1024
	ds_read_b128 v[176:179], v167 offset:2048
	ds_read_b128 v[180:183], v167 offset:3072
	v_add_u32_e32 v167, s67, v158
	ds_read_b128 v[186:189], v167
	ds_read_b128 v[190:193], v167 offset:1024
	ds_read_b128 v[194:197], v167 offset:2048
	ds_read_b128 v[198:201], v167 offset:3072
	s_add_u32 s44, s44, 0x40000
	s_addc_u32 s45, s45, 0
	s_mov_b32 m0, s51
	v_lshl_add_u64 v[242:243], s[44:45], 0, v[136:137]
	ds_read_b128 v[202:205], v160 offset:32768
	ds_read_b128 v[206:209], v160 offset:33792
	ds_read_b128 v[210:213], v160 offset:34816
	ds_read_b128 v[214:217], v160 offset:35840
	ds_read_b128 v[218:221], v160 offset:36864
	ds_read_b128 v[222:225], v160 offset:37888
	ds_read_b128 v[226:229], v160 offset:38912
	ds_read_b128 v[230:233], v160 offset:39936
	global_load_lds_dwordx4 v[242:243], off
	v_lshl_add_u64 v[242:243], s[44:45], 0, v[132:133]
	s_mov_b32 m0, s52
	s_nop 0
	global_load_lds_dwordx4 v[242:243], off
	s_waitcnt vmcnt(8)
	s_waitcnt lgkmcnt(0)
	s_barrier
	s_setprio 1
	s_waitcnt lgkmcnt(0)
	v_mfma_f32_16x16x32_bf16 v[126:129], v[168:171], v[202:205], v[126:129]
	v_mfma_f32_16x16x32_bf16 v[118:121], v[176:179], v[202:205], v[118:121]
	v_mfma_f32_16x16x32_bf16 v[110:113], v[168:171], v[210:213], v[110:113]
	v_mfma_f32_16x16x32_bf16 v[102:105], v[176:179], v[210:213], v[102:105]
	v_mfma_f32_16x16x32_bf16 v[94:97], v[168:171], v[218:221], v[94:97]
	v_mfma_f32_16x16x32_bf16 v[86:89], v[176:179], v[218:221], v[86:89]
	v_mfma_f32_16x16x32_bf16 v[78:81], v[168:171], v[226:229], v[78:81]
	v_mfma_f32_16x16x32_bf16 v[70:73], v[176:179], v[226:229], v[70:73]
	v_mfma_f32_16x16x32_bf16 v[126:129], v[172:175], v[206:209], v[126:129]
	v_mfma_f32_16x16x32_bf16 v[118:121], v[180:183], v[206:209], v[118:121]
	v_mfma_f32_16x16x32_bf16 v[110:113], v[172:175], v[214:217], v[110:113]
	v_mfma_f32_16x16x32_bf16 v[102:105], v[180:183], v[214:217], v[102:105]
	v_mfma_f32_16x16x32_bf16 v[94:97], v[172:175], v[222:225], v[94:97]
	v_mfma_f32_16x16x32_bf16 v[86:89], v[180:183], v[222:225], v[86:89]
	v_mfma_f32_16x16x32_bf16 v[78:81], v[172:175], v[230:233], v[78:81]
	v_mfma_f32_16x16x32_bf16 v[70:73], v[180:183], v[230:233], v[70:73]
	s_setprio 0
	s_setprio 1
	v_mfma_f32_16x16x32_bf16 v[122:125], v[186:189], v[202:205], v[122:125]
	v_mfma_f32_16x16x32_bf16 v[114:117], v[194:197], v[202:205], v[114:117]
	v_mfma_f32_16x16x32_bf16 v[106:109], v[186:189], v[210:213], v[106:109]
	v_mfma_f32_16x16x32_bf16 v[98:101], v[194:197], v[210:213], v[98:101]
	v_mfma_f32_16x16x32_bf16 v[90:93], v[186:189], v[218:221], v[90:93]
	v_mfma_f32_16x16x32_bf16 v[82:85], v[194:197], v[218:221], v[82:85]
	v_mfma_f32_16x16x32_bf16 v[74:77], v[186:189], v[226:229], v[74:77]
	v_mfma_f32_16x16x32_bf16 v[66:69], v[194:197], v[226:229], v[66:69]
	v_mfma_f32_16x16x32_bf16 v[122:125], v[190:193], v[206:209], v[122:125]
	v_mfma_f32_16x16x32_bf16 v[114:117], v[198:201], v[206:209], v[114:117]
	v_mfma_f32_16x16x32_bf16 v[106:109], v[190:193], v[214:217], v[106:109]
	v_mfma_f32_16x16x32_bf16 v[98:101], v[198:201], v[214:217], v[98:101]
	v_mfma_f32_16x16x32_bf16 v[90:93], v[190:193], v[222:225], v[90:93]
	v_mfma_f32_16x16x32_bf16 v[82:85], v[198:201], v[222:225], v[82:85]
	v_mfma_f32_16x16x32_bf16 v[74:77], v[190:193], v[230:233], v[74:77]
	v_mfma_f32_16x16x32_bf16 v[66:69], v[198:201], v[230:233], v[66:69]
	s_setprio 0
	s_barrier
; #define PG8_STAGE(bufoff, gbase, voff) do { _Pragma("unroll") for (int _i = 0; _i < 2; ++_i) \
;         __builtin_amdgcn_global_load_lds((const unsigned*)((const char*)(gbase) + (voff)[_i]), (LAS unsigned*)(lds + (bufoff) + ldsw + _i * 8192), 16, 0, 0); } while (0)
; #define PG8_LDA(dst, b, h) do { _Pragma("unroll") for (int m = 0; m < 4; ++m) _Pragma("unroll") for (int k = 0; k < 2; ++k) dst[m][k] = *(const LAS bf16x8*)(lds + PG8_SA(b, h) + aoff + m * 2048 + k * 1024); } while (0)
; #define PG8_MMA(ai, bj, At, Bt) do { __builtin_amdgcn_s_setprio(1); _Pragma("unroll") for (int m = 0; m < 4; ++m) _Pragma("unroll") for (int n = 0; n < 2; ++n) _Pragma("unroll") for (int k = 0; k < 2; ++k) \
;         acc[ai][bj][m][n] = __builtin_amdgcn_mfma_f32_16x16x32_bf16(Bt[n][k], At[m][k], acc[ai][bj][m][n], 0, 0, 0); __builtin_amdgcn_s_setprio(0); } while (0)
; #define PG8_WAIT_V(n) asm volatile("s_waitcnt vmcnt(" #n ")" ::: "memory")
; #define PG8_WAIT_L(n) asm volatile("s_waitcnt lgkmcnt(" #n ")" ::: "memory")
; #define PG8_BAR __builtin_amdgcn_s_barrier()
; #define PG8_SCHED __builtin_amdgcn_sched_barrier(0)
; template <class Epi, class Sched>
; DI void gemm_phase(LAS unsigned char* lds, const Gemm g, const Sched& S, const Epi& E) {
;     ...
;             PG8_WAIT_V(8); PG8_WAIT_L(0); PG8_BAR; PG8_MMA(0, 0, At, B0); PG8_MMA(0, 1, At, B1); PG8_BAR; PG8_SCHED;
;             PG8_LDA(At, 1, 1); PG8_STAGE(PG8_SB(1, 0), b3, voffB); PG8_STAGE(PG8_SB(1, 1), b3 + hstepB, voffB); PG8_STAGE(PG8_SA(1, 0), a3, voffA);
;             PG8_WAIT_V(8); PG8_WAIT_L(0); PG8_BAR; PG8_MMA(1, 0, At, B0); PG8_MMA(1, 1, At, B1); PG8_BAR; PG8_SCHED;
;         }
	s_add_i32 s44, s66, s46
	v_lshl_add_u64 v[234:235], v[234:235], 0, s[16:17]
	s_mov_b32 m0, s44
	ds_read_b128 v[202:205], v160 offset:49152
	ds_read_b128 v[206:209], v160 offset:50176
	ds_read_b128 v[210:213], v160 offset:51200
	ds_read_b128 v[214:217], v160 offset:52224
	ds_read_b128 v[218:221], v160 offset:53248
	ds_read_b128 v[222:225], v160 offset:54272
	ds_read_b128 v[226:229], v160 offset:55296
	ds_read_b128 v[230:233], v160 offset:56320
	global_load_lds_dwordx4 v[234:235], off
	s_add_i32 m0, s44, 0x2000
	s_add_u32 s42, s42, 0x40080
	v_lshl_add_u64 v[234:235], v[236:237], 0, s[16:17]
	s_addc_u32 s43, s43, 0
	s_add_i32 s44, s67, s46
	global_load_lds_dwordx4 v[234:235], off
	v_lshl_add_u64 v[234:235], s[42:43], 0, v[134:135]
	s_mov_b32 m0, s44
	s_nop 0
	global_load_lds_dwordx4 v[234:235], off
	v_lshl_add_u64 v[234:235], s[42:43], 0, v[130:131]
	s_add_i32 m0, s44, 0x2000
	s_nop 0
	global_load_lds_dwordx4 v[234:235], off
	v_lshl_add_u64 v[234:235], v[238:239], 0, s[16:17]
	s_mov_b32 m0, s54
	s_nop 0
	global_load_lds_dwordx4 v[234:235], off
	v_lshl_add_u64 v[234:235], v[240:241], 0, s[16:17]
	s_mov_b32 m0, s55
	s_nop 0
	global_load_lds_dwordx4 v[234:235], off
	s_waitcnt vmcnt(8)
	s_waitcnt lgkmcnt(0)
	s_barrier
	s_setprio 1
	s_waitcnt lgkmcnt(0)
	v_mfma_f32_16x16x32_bf16 v[62:65], v[168:171], v[202:205], v[62:65]
	v_mfma_f32_16x16x32_bf16 v[54:57], v[176:179], v[202:205], v[54:57]
	v_mfma_f32_16x16x32_bf16 v[46:49], v[168:171], v[210:213], v[46:49]
	v_mfma_f32_16x16x32_bf16 v[38:41], v[176:179], v[210:213], v[38:41]
	v_mfma_f32_16x16x32_bf16 v[30:33], v[168:171], v[218:221], v[30:33]
	v_mfma_f32_16x16x32_bf16 v[22:25], v[176:179], v[218:221], v[22:25]
	v_mfma_f32_16x16x32_bf16 v[14:17], v[168:171], v[226:229], v[14:17]
	v_mfma_f32_16x16x32_bf16 v[6:9], v[176:179], v[226:229], v[6:9]
	v_mfma_f32_16x16x32_bf16 v[62:65], v[172:175], v[206:209], v[62:65]
	v_mfma_f32_16x16x32_bf16 v[54:57], v[180:183], v[206:209], v[54:57]
	v_mfma_f32_16x16x32_bf16 v[46:49], v[172:175], v[214:217], v[46:49]
	v_mfma_f32_16x16x32_bf16 v[38:41], v[180:183], v[214:217], v[38:41]
	v_mfma_f32_16x16x32_bf16 v[30:33], v[172:175], v[222:225], v[30:33]
	v_mfma_f32_16x16x32_bf16 v[22:25], v[180:183], v[222:225], v[22:25]
	v_mfma_f32_16x16x32_bf16 v[14:17], v[172:175], v[230:233], v[14:17]
	v_mfma_f32_16x16x32_bf16 v[6:9], v[180:183], v[230:233], v[6:9]
	s_setprio 0
	s_setprio 1
	v_mfma_f32_16x16x32_bf16 v[58:61], v[186:189], v[202:205], v[58:61]
	v_mfma_f32_16x16x32_bf16 v[50:53], v[194:197], v[202:205], v[50:53]
	v_mfma_f32_16x16x32_bf16 v[42:45], v[186:189], v[210:213], v[42:45]
	v_mfma_f32_16x16x32_bf16 v[34:37], v[194:197], v[210:213], v[34:37]
	v_mfma_f32_16x16x32_bf16 v[26:29], v[186:189], v[218:221], v[26:29]
	v_mfma_f32_16x16x32_bf16 v[18:21], v[194:197], v[218:221], v[18:21]
	v_mfma_f32_16x16x32_bf16 v[10:13], v[186:189], v[226:229], v[10:13]
	v_mfma_f32_16x16x32_bf16 v[2:5], v[194:197], v[226:229], v[2:5]
	v_mfma_f32_16x16x32_bf16 v[58:61], v[190:193], v[206:209], v[58:61]
	v_mfma_f32_16x16x32_bf16 v[50:53], v[198:201], v[206:209], v[50:53]
	v_mfma_f32_16x16x32_bf16 v[42:45], v[190:193], v[214:217], v[42:45]
	v_mfma_f32_16x16x32_bf16 v[34:37], v[198:201], v[214:217], v[34:37]
	v_mfma_f32_16x16x32_bf16 v[26:29], v[190:193], v[222:225], v[26:29]
	v_mfma_f32_16x16x32_bf16 v[18:21], v[198:201], v[222:225], v[18:21]
	v_mfma_f32_16x16x32_bf16 v[10:13], v[190:193], v[230:233], v[10:13]
	v_mfma_f32_16x16x32_bf16 v[2:5], v[198:201], v[230:233], v[2:5]
	s_setprio 0
	s_barrier
	s_add_i32 s65, s65, 2
	s_add_u32 s40, s40, 0x100
	s_addc_u32 s41, s41, 0
	s_add_u32 s63, s63, 0x100
	s_addc_u32 s64, s64, 0
	s_cmp_gt_u32 s65, 13

; #define PG8_STAGE(bufoff, gbase, voff) do { _Pragma("unroll") for (int _i = 0; _i < 2; ++_i) \
;         __builtin_amdgcn_global_load_lds((const unsigned*)((const char*)(gbase) + (voff)[_i]), (LAS unsigned*)(lds + (bufoff) + ldsw + _i * 8192), 16, 0, 0); } while (0)
; #define PG8_LDA(dst, b, h) do { _Pragma("unroll") for (int m = 0; m < 4; ++m) _Pragma("unroll") for (int k = 0; k < 2; ++k) dst[m][k] = *(const LAS bf16x8*)(lds + PG8_SA(b, h) + aoff + m * 2048 + k * 1024); } while (0)
; #define PG8_LDB(dst, b, h) do { _Pragma("unroll") for (int n = 0; n < 2; ++n) _Pragma("unroll") for (int k = 0; k < 2; ++k) dst[n][k] = *(const LAS bf16x8*)(lds + PG8_SB(b, h) + boff + n * 2048 + k * 1024); } while (0)
; #define PG8_MMA(ai, bj, At, Bt) do { __builtin_amdgcn_s_setprio(1); _Pragma("unroll") for (int m = 0; m < 4; ++m) _Pragma("unroll") for (int n = 0; n < 2; ++n) _Pragma("unroll") for (int k = 0; k < 2; ++k) \
;         acc[ai][bj][m][n] = __builtin_amdgcn_mfma_f32_16x16x32_bf16(Bt[n][k], At[m][k], acc[ai][bj][m][n], 0, 0, 0); __builtin_amdgcn_s_setprio(0); } while (0)
; #define PG8_WAIT_V(n) asm volatile("s_waitcnt vmcnt(" #n ")" ::: "memory")
; template <class Epi, class Sched>
; DI void gemm_phase(LAS unsigned char* lds, const Gemm g, const Sched& S, const Epi& E) {
;     ...
;         const char* nA = has_next ? (const char*)(nxt.src ? g.A1 : g.A0) + (size_t)nxt.pm * tstepA : cA; const char* nB = has_next ? (const char*)(nxt.src ? g.B1 : g.B0) + (size_t)nxt.pn * tstepB : cB;
;         for (int t = 0; t < nt; t += 2) {
;             const bool last = (t == nt - 2);
;             const char* a1 = cA + (size_t)(t + 1) * kstep;
;             const char* a2 = last ? nA : cA + (size_t)(t + 2) * kstep; const char* b2 = last ? nB : cB + (size_t)(t + 2) * kstep;
;             const char* a3 = a2 + kstep; const char* b3 = b2 + kstep;
;             PG8_LDB(B0, 0, 0); PG8_LDB(B1, 0, 1); PG8_SCHED; PG8_LDA(At, 0, 0); PG8_STAGE(PG8_SA(1, 1), a1 + hstepA, voffA);
;             PG8_WAIT_V(8); PG8_WAIT_L(0); PG8_BAR; PG8_MMA(0, 0, At, B0); PG8_MMA(0, 1, At, B1); PG8_BAR; PG8_SCHED;
;             PG8_LDA(At, 0, 1); PG8_STAGE(PG8_SB(0, 0), b2, voffB); PG8_STAGE(PG8_SB(0, 1), b2 + hstepB, voffB); PG8_STAGE(PG8_SA(0, 0), a2, voffA);
;             PG8_WAIT_V(8); PG8_WAIT_L(0); PG8_BAR; PG8_MMA(1, 0, At, B0); PG8_MMA(1, 1, At, B1); PG8_BAR; PG8_SCHED;
.LBB0_277:
	s_add_u32 s36, s36, 0xb0080
	s_addc_u32 s37, s37, 0
	s_add_u32 s60, s38, 0x100
	s_addc_u32 s61, s39, 0
	s_mov_b32 s62, -2
	s_waitcnt lgkmcnt(0)
	ds_read_b128 v[148:151], v154
	ds_read_b128 v[158:161], v154 offset:1024
	ds_read_b128 v[162:165], v154 offset:2048
	ds_read_b128 v[166:169], v154 offset:3072
	ds_read_b128 v[170:173], v155
	ds_read_b128 v[174:177], v155 offset:1024
	ds_read_b128 v[178:181], v155 offset:2048
	ds_read_b128 v[186:189], v155 offset:3072
	s_add_u32 s38, s36, 0xfff50080
	s_addc_u32 s39, s37, -1
	s_cmp_eq_u32 s62, 40
	s_cselect_b32 s41, s9, s39
	s_cselect_b32 s40, s8, s38
	s_cselect_b32 s39, s35, s61
	s_cselect_b32 s38, s34, s60
	v_lshl_add_u64 v[182:183], s[36:37], 0, v[138:139]
	s_add_i32 m0, s45, 0xc000
	ds_read_b128 v[190:193], v156
	ds_read_b128 v[194:197], v156 offset:1024
	ds_read_b128 v[198:201], v156 offset:2048
	ds_read_b128 v[202:205], v156 offset:3072
	ds_read_b128 v[206:209], v156 offset:4096
	ds_read_b128 v[210:213], v156 offset:5120
	ds_read_b128 v[214:217], v156 offset:6144
	ds_read_b128 v[218:221], v156 offset:7168
	global_load_lds_dwordx4 v[182:183], off
	v_lshl_add_u64 v[182:183], s[36:37], 0, v[140:141]
	s_add_i32 m0, s45, 0xe000
	s_nop 0
	global_load_lds_dwordx4 v[182:183], off
	s_waitcnt vmcnt(8)
	s_waitcnt lgkmcnt(0)
	s_barrier
	s_setprio 1
	s_waitcnt lgkmcnt(0)
	v_mfma_f32_16x16x32_bf16 v[126:129], v[148:151], v[190:193], 0
	v_mfma_f32_16x16x32_bf16 v[122:125], v[162:165], v[190:193], 0
	v_mfma_f32_16x16x32_bf16 v[110:113], v[148:151], v[198:201], 0
	v_mfma_f32_16x16x32_bf16 v[106:109], v[162:165], v[198:201], 0
	v_mfma_f32_16x16x32_bf16 v[94:97], v[148:151], v[206:209], 0
	v_mfma_f32_16x16x32_bf16 v[90:93], v[162:165], v[206:209], 0
	v_mfma_f32_16x16x32_bf16 v[78:81], v[148:151], v[214:217], 0
	v_mfma_f32_16x16x32_bf16 v[74:77], v[162:165], v[214:217], 0
	v_mfma_f32_16x16x32_bf16 v[126:129], v[158:161], v[194:197], v[126:129]
	v_mfma_f32_16x16x32_bf16 v[122:125], v[166:169], v[194:197], v[122:125]
	v_mfma_f32_16x16x32_bf16 v[110:113], v[158:161], v[202:205], v[110:113]
	v_mfma_f32_16x16x32_bf16 v[106:109], v[166:169], v[202:205], v[106:109]
	v_mfma_f32_16x16x32_bf16 v[94:97], v[158:161], v[210:213], v[94:97]
	v_mfma_f32_16x16x32_bf16 v[90:93], v[166:169], v[210:213], v[90:93]
	v_mfma_f32_16x16x32_bf16 v[78:81], v[158:161], v[218:221], v[78:81]
	v_mfma_f32_16x16x32_bf16 v[74:77], v[166:169], v[218:221], v[74:77]
	s_setprio 0
	s_setprio 1
	v_mfma_f32_16x16x32_bf16 v[118:121], v[170:173], v[190:193], 0
	v_mfma_f32_16x16x32_bf16 v[114:117], v[178:181], v[190:193], 0
	v_mfma_f32_16x16x32_bf16 v[102:105], v[170:173], v[198:201], 0
	v_mfma_f32_16x16x32_bf16 v[98:101], v[178:181], v[198:201], 0
	v_mfma_f32_16x16x32_bf16 v[86:89], v[170:173], v[206:209], 0
	v_mfma_f32_16x16x32_bf16 v[82:85], v[178:181], v[206:209], 0
	v_mfma_f32_16x16x32_bf16 v[70:73], v[170:173], v[214:217], 0
	v_mfma_f32_16x16x32_bf16 v[66:69], v[178:181], v[214:217], 0
	v_mfma_f32_16x16x32_bf16 v[118:121], v[174:177], v[194:197], v[118:121]
	v_mfma_f32_16x16x32_bf16 v[114:117], v[186:189], v[194:197], v[114:117]
	v_mfma_f32_16x16x32_bf16 v[102:105], v[174:177], v[202:205], v[102:105]
	v_mfma_f32_16x16x32_bf16 v[98:101], v[186:189], v[202:205], v[98:101]
	v_mfma_f32_16x16x32_bf16 v[86:89], v[174:177], v[210:213], v[86:89]
	v_mfma_f32_16x16x32_bf16 v[82:85], v[186:189], v[210:213], v[82:85]
	v_mfma_f32_16x16x32_bf16 v[70:73], v[174:177], v[218:221], v[70:73]
	v_mfma_f32_16x16x32_bf16 v[66:69], v[186:189], v[218:221], v[66:69]
	s_setprio 0
	s_barrier
	s_add_i32 s63, s54, s44
	v_lshl_add_u64 v[182:183], s[38:39], 0, v[132:133]
	s_mov_b32 m0, s63
	ds_read_b128 v[190:193], v156 offset:16384
	ds_read_b128 v[194:197], v156 offset:17408
	ds_read_b128 v[198:201], v156 offset:18432
	ds_read_b128 v[202:205], v156 offset:19456
	ds_read_b128 v[206:209], v156 offset:20480
	ds_read_b128 v[210:213], v156 offset:21504
	ds_read_b128 v[214:217], v156 offset:22528
	ds_read_b128 v[218:221], v156 offset:23552
	global_load_lds_dwordx4 v[182:183], off
	s_add_i32 m0, s63, 0x2000
	s_add_u32 s64, s38, 0xb0000
	v_lshl_add_u64 v[222:223], s[38:39], 0, v[136:137]
	s_addc_u32 s65, s39, 0
	s_add_i32 s63, s55, s44
	global_load_lds_dwordx4 v[222:223], off
	v_lshl_add_u64 v[224:225], s[64:65], 0, v[132:133]
	s_mov_b32 m0, s63
	v_lshl_add_u64 v[226:227], s[40:41], 0, v[134:135]
	global_load_lds_dwordx4 v[224:225], off
	v_lshl_add_u64 v[224:225], s[64:65], 0, v[136:137]
	s_add_i32 m0, s63, 0x2000
	s_nop 0
	global_load_lds_dwordx4 v[224:225], off
	v_lshl_add_u64 v[224:225], s[40:41], 0, v[130:131]
	s_mov_b32 m0, s45
	s_nop 0
	global_load_lds_dwordx4 v[224:225], off
	s_mov_b32 m0, s46
	s_nop 0
	global_load_lds_dwordx4 v[226:227], off
	s_waitcnt vmcnt(8)
	s_waitcnt lgkmcnt(0)
	s_barrier
; #define PG8_STAGE(bufoff, gbase, voff) do { _Pragma("unroll") for (int _i = 0; _i < 2; ++_i) \
;         __builtin_amdgcn_global_load_lds((const unsigned*)((const char*)(gbase) + (voff)[_i]), (LAS unsigned*)(lds + (bufoff) + ldsw + _i * 8192), 16, 0, 0); } while (0)
; #define PG8_LDA(dst, b, h) do { _Pragma("unroll") for (int m = 0; m < 4; ++m) _Pragma("unroll") for (int k = 0; k < 2; ++k) dst[m][k] = *(const LAS bf16x8*)(lds + PG8_SA(b, h) + aoff + m * 2048 + k * 1024); } while (0)
; #define PG8_LDB(dst, b, h) do { _Pragma("unroll") for (int n = 0; n < 2; ++n) _Pragma("unroll") for (int k = 0; k < 2; ++k) dst[n][k] = *(const LAS bf16x8*)(lds + PG8_SB(b, h) + boff + n * 2048 + k * 1024); } while (0)
; #define PG8_MMA(ai, bj, At, Bt) do { __builtin_amdgcn_s_setprio(1); _Pragma("unroll") for (int m = 0; m < 4; ++m) _Pragma("unroll") for (int n = 0; n < 2; ++n) _Pragma("unroll") for (int k = 0; k < 2; ++k) \
;         acc[ai][bj][m][n] = __builtin_amdgcn_mfma_f32_16x16x32_bf16(Bt[n][k], At[m][k], acc[ai][bj][m][n], 0, 0, 0); __builtin_amdgcn_s_setprio(0); } while (0)
; #define PG8_WAIT_V(n) asm volatile("s_waitcnt vmcnt(" #n ")" ::: "memory")
; #define PG8_WAIT_L(n) asm volatile("s_waitcnt lgkmcnt(" #n ")" ::: "memory")
; #define PG8_BAR __builtin_amdgcn_s_barrier()
; #define PG8_SCHED __builtin_amdgcn_sched_barrier(0)
; template <class Epi, class Sched>
; DI void gemm_phase(LAS unsigned char* lds, const Gemm g, const Sched& S, const Epi& E) {
;     ...
;             PG8_WAIT_V(8); PG8_WAIT_L(0); PG8_BAR; PG8_MMA(1, 0, At, B0); PG8_MMA(1, 1, At, B1); PG8_BAR; PG8_SCHED;
;             PG8_LDB(B0, 1, 0); PG8_LDB(B1, 1, 1); PG8_SCHED; PG8_LDA(At, 1, 0); PG8_STAGE(PG8_SA(0, 1), a2 + hstepA, voffA);
;             PG8_WAIT_V(8); PG8_WAIT_L(0); PG8_BAR; PG8_MMA(0, 0, At, B0); PG8_MMA(0, 1, At, B1); PG8_BAR; PG8_SCHED;
	s_setprio 1
	s_waitcnt lgkmcnt(0)
	v_mfma_f32_16x16x32_bf16 v[62:65], v[148:151], v[190:193], 0
	v_mfma_f32_16x16x32_bf16 v[58:61], v[162:165], v[190:193], 0
	v_mfma_f32_16x16x32_bf16 v[46:49], v[148:151], v[198:201], 0
	v_mfma_f32_16x16x32_bf16 v[42:45], v[162:165], v[198:201], 0
	v_mfma_f32_16x16x32_bf16 v[30:33], v[148:151], v[206:209], 0
	v_mfma_f32_16x16x32_bf16 v[26:29], v[162:165], v[206:209], 0
	v_mfma_f32_16x16x32_bf16 v[14:17], v[148:151], v[214:217], 0
	v_mfma_f32_16x16x32_bf16 v[10:13], v[162:165], v[214:217], 0
	v_mfma_f32_16x16x32_bf16 v[62:65], v[158:161], v[194:197], v[62:65]
	v_mfma_f32_16x16x32_bf16 v[58:61], v[166:169], v[194:197], v[58:61]
	v_mfma_f32_16x16x32_bf16 v[46:49], v[158:161], v[202:205], v[46:49]
	v_mfma_f32_16x16x32_bf16 v[42:45], v[166:169], v[202:205], v[42:45]
	v_mfma_f32_16x16x32_bf16 v[30:33], v[158:161], v[210:213], v[30:33]
	v_mfma_f32_16x16x32_bf16 v[26:29], v[166:169], v[210:213], v[26:29]
	v_mfma_f32_16x16x32_bf16 v[14:17], v[158:161], v[218:221], v[14:17]
	v_mfma_f32_16x16x32_bf16 v[10:13], v[166:169], v[218:221], v[10:13]
	s_setprio 0
	s_setprio 1
	v_mfma_f32_16x16x32_bf16 v[54:57], v[170:173], v[190:193], 0
	v_mfma_f32_16x16x32_bf16 v[50:53], v[178:181], v[190:193], 0
	v_mfma_f32_16x16x32_bf16 v[38:41], v[170:173], v[198:201], 0
	v_mfma_f32_16x16x32_bf16 v[34:37], v[178:181], v[198:201], 0
	v_mfma_f32_16x16x32_bf16 v[22:25], v[170:173], v[206:209], 0
	v_mfma_f32_16x16x32_bf16 v[18:21], v[178:181], v[206:209], 0
	v_mfma_f32_16x16x32_bf16 v[6:9], v[170:173], v[214:217], 0
	v_mfma_f32_16x16x32_bf16 v[2:5], v[178:181], v[214:217], 0
	v_mfma_f32_16x16x32_bf16 v[54:57], v[174:177], v[194:197], v[54:57]
	v_mfma_f32_16x16x32_bf16 v[50:53], v[186:189], v[194:197], v[50:53]
	v_mfma_f32_16x16x32_bf16 v[38:41], v[174:177], v[202:205], v[38:41]
	v_mfma_f32_16x16x32_bf16 v[34:37], v[186:189], v[202:205], v[34:37]
	v_mfma_f32_16x16x32_bf16 v[22:25], v[174:177], v[210:213], v[22:25]
	v_mfma_f32_16x16x32_bf16 v[18:21], v[186:189], v[210:213], v[18:21]
	v_mfma_f32_16x16x32_bf16 v[6:9], v[174:177], v[218:221], v[6:9]
	v_mfma_f32_16x16x32_bf16 v[2:5], v[186:189], v[218:221], v[2:5]
	s_setprio 0
	s_barrier
	s_add_i32 s63, 0, 0x18000
	s_add_i32 s64, 0, 0x1c000
	v_add_u32_e32 v166, s63, v152
	v_add_u32_e32 v185, s64, v152
	ds_read_b128 v[148:151], v166
	ds_read_b128 v[158:161], v166 offset:1024
	ds_read_b128 v[162:165], v166 offset:2048
	ds_read_b128 v[166:169], v166 offset:3072
	ds_read_b128 v[170:173], v185
	ds_read_b128 v[174:177], v185 offset:1024
	ds_read_b128 v[178:181], v185 offset:2048
	ds_read_b128 v[186:189], v185 offset:3072
	s_add_u32 s40, s40, 0xb0000
	s_addc_u32 s41, s41, 0
	s_mov_b32 m0, s47
	v_lshl_add_u64 v[228:229], s[40:41], 0, v[130:131]
	ds_read_b128 v[190:193], v156 offset:32768
	ds_read_b128 v[194:197], v156 offset:33792
	ds_read_b128 v[198:201], v156 offset:34816
	ds_read_b128 v[202:205], v156 offset:35840
	ds_read_b128 v[206:209], v156 offset:36864
	ds_read_b128 v[210:213], v156 offset:37888
	ds_read_b128 v[214:217], v156 offset:38912
	ds_read_b128 v[218:221], v156 offset:39936
	global_load_lds_dwordx4 v[228:229], off
	v_lshl_add_u64 v[228:229], s[40:41], 0, v[134:135]
	s_mov_b32 m0, s48
	s_nop 0
	global_load_lds_dwordx4 v[228:229], off
	s_waitcnt vmcnt(8)
	s_waitcnt lgkmcnt(0)
	s_barrier
	s_setprio 1
	s_waitcnt lgkmcnt(0)
	v_mfma_f32_16x16x32_bf16 v[126:129], v[148:151], v[190:193], v[126:129]
	v_mfma_f32_16x16x32_bf16 v[122:125], v[162:165], v[190:193], v[122:125]
	v_mfma_f32_16x16x32_bf16 v[110:113], v[148:151], v[198:201], v[110:113]
	v_mfma_f32_16x16x32_bf16 v[106:109], v[162:165], v[198:201], v[106:109]
	v_mfma_f32_16x16x32_bf16 v[94:97], v[148:151], v[206:209], v[94:97]
	v_mfma_f32_16x16x32_bf16 v[90:93], v[162:165], v[206:209], v[90:93]
	v_mfma_f32_16x16x32_bf16 v[78:81], v[148:151], v[214:217], v[78:81]
	v_mfma_f32_16x16x32_bf16 v[74:77], v[162:165], v[214:217], v[74:77]
	v_mfma_f32_16x16x32_bf16 v[126:129], v[158:161], v[194:197], v[126:129]
	v_mfma_f32_16x16x32_bf16 v[122:125], v[166:169], v[194:197], v[122:125]
	v_mfma_f32_16x16x32_bf16 v[110:113], v[158:161], v[202:205], v[110:113]
	v_mfma_f32_16x16x32_bf16 v[106:109], v[166:169], v[202:205], v[106:109]
	v_mfma_f32_16x16x32_bf16 v[94:97], v[158:161], v[210:213], v[94:97]
	v_mfma_f32_16x16x32_bf16 v[90:93], v[166:169], v[210:213], v[90:93]
	v_mfma_f32_16x16x32_bf16 v[78:81], v[158:161], v[218:221], v[78:81]
	v_mfma_f32_16x16x32_bf16 v[74:77], v[166:169], v[218:221], v[74:77]
	s_setprio 0
	s_setprio 1
	v_mfma_f32_16x16x32_bf16 v[118:121], v[170:173], v[190:193], v[118:121]
	v_mfma_f32_16x16x32_bf16 v[114:117], v[178:181], v[190:193], v[114:117]
	v_mfma_f32_16x16x32_bf16 v[102:105], v[170:173], v[198:201], v[102:105]
	v_mfma_f32_16x16x32_bf16 v[98:101], v[178:181], v[198:201], v[98:101]
	v_mfma_f32_16x16x32_bf16 v[86:89], v[170:173], v[206:209], v[86:89]
	v_mfma_f32_16x16x32_bf16 v[82:85], v[178:181], v[206:209], v[82:85]
	v_mfma_f32_16x16x32_bf16 v[70:73], v[170:173], v[214:217], v[70:73]
	v_mfma_f32_16x16x32_bf16 v[66:69], v[178:181], v[214:217], v[66:69]
	v_mfma_f32_16x16x32_bf16 v[118:121], v[174:177], v[194:197], v[118:121]
	v_mfma_f32_16x16x32_bf16 v[114:117], v[186:189], v[194:197], v[114:117]
	v_mfma_f32_16x16x32_bf16 v[102:105], v[174:177], v[202:205], v[102:105]
	v_mfma_f32_16x16x32_bf16 v[98:101], v[186:189], v[202:205], v[98:101]
	v_mfma_f32_16x16x32_bf16 v[86:89], v[174:177], v[210:213], v[86:89]
	v_mfma_f32_16x16x32_bf16 v[82:85], v[186:189], v[210:213], v[82:85]
	v_mfma_f32_16x16x32_bf16 v[70:73], v[174:177], v[218:221], v[70:73]
	v_mfma_f32_16x16x32_bf16 v[66:69], v[186:189], v[218:221], v[66:69]
	s_setprio 0
	s_barrier
; #define PG8_STAGE(bufoff, gbase, voff) do { _Pragma("unroll") for (int _i = 0; _i < 2; ++_i) \
;         __builtin_amdgcn_global_load_lds((const unsigned*)((const char*)(gbase) + (voff)[_i]), (LAS unsigned*)(lds + (bufoff) + ldsw + _i * 8192), 16, 0, 0); } while (0)
; #define PG8_LDA(dst, b, h) do { _Pragma("unroll") for (int m = 0; m < 4; ++m) _Pragma("unroll") for (int k = 0; k < 2; ++k) dst[m][k] = *(const LAS bf16x8*)(lds + PG8_SA(b, h) + aoff + m * 2048 + k * 1024); } while (0)
; #define PG8_MMA(ai, bj, At, Bt) do { __builtin_amdgcn_s_setprio(1); _Pragma("unroll") for (int m = 0; m < 4; ++m) _Pragma("unroll") for (int n = 0; n < 2; ++n) _Pragma("unroll") for (int k = 0; k < 2; ++k) \
;         acc[ai][bj][m][n] = __builtin_amdgcn_mfma_f32_16x16x32_bf16(Bt[n][k], At[m][k], acc[ai][bj][m][n], 0, 0, 0); __builtin_amdgcn_s_setprio(0); } while (0)
; #define PG8_WAIT_V(n) asm volatile("s_waitcnt vmcnt(" #n ")" ::: "memory")
; #define PG8_WAIT_L(n) asm volatile("s_waitcnt lgkmcnt(" #n ")" ::: "memory")
; #define PG8_BAR __builtin_amdgcn_s_barrier()
; #define PG8_SCHED __builtin_amdgcn_sched_barrier(0)
; template <class Epi, class Sched>
; DI void gemm_phase(LAS unsigned char* lds, const Gemm g, const Sched& S, const Epi& E) {
;     ...
;             PG8_WAIT_V(8); PG8_WAIT_L(0); PG8_BAR; PG8_MMA(0, 0, At, B0); PG8_MMA(0, 1, At, B1); PG8_BAR; PG8_SCHED;
;             PG8_LDA(At, 1, 1); PG8_STAGE(PG8_SB(1, 0), b3, voffB); PG8_STAGE(PG8_SB(1, 1), b3 + hstepB, voffB); PG8_STAGE(PG8_SA(1, 0), a3, voffA);
;             PG8_WAIT_V(8); PG8_WAIT_L(0); PG8_BAR; PG8_MMA(1, 0, At, B0); PG8_MMA(1, 1, At, B1); PG8_BAR; PG8_SCHED;
;         }
	s_add_i32 s40, s63, s44
	v_lshl_add_u64 v[182:183], v[182:183], 0, s[16:17]
	s_mov_b32 m0, s40
	ds_read_b128 v[190:193], v156 offset:49152
	ds_read_b128 v[194:197], v156 offset:50176
	ds_read_b128 v[198:201], v156 offset:51200
	ds_read_b128 v[202:205], v156 offset:52224
	ds_read_b128 v[206:209], v156 offset:53248
	ds_read_b128 v[210:213], v156 offset:54272
	ds_read_b128 v[214:217], v156 offset:55296
	ds_read_b128 v[218:221], v156 offset:56320
	global_load_lds_dwordx4 v[182:183], off
	s_add_i32 m0, s40, 0x2000
	s_add_u32 s38, s38, 0xb0080
	v_lshl_add_u64 v[182:183], v[222:223], 0, s[16:17]
	s_addc_u32 s39, s39, 0
	s_add_i32 s40, s64, s44
	global_load_lds_dwordx4 v[182:183], off
	v_lshl_add_u64 v[182:183], s[38:39], 0, v[132:133]
	s_mov_b32 m0, s40
	s_nop 0
	global_load_lds_dwordx4 v[182:183], off
	v_lshl_add_u64 v[182:183], s[38:39], 0, v[136:137]
	s_add_i32 m0, s40, 0x2000
	s_nop 0
	global_load_lds_dwordx4 v[182:183], off
	v_lshl_add_u64 v[182:183], v[224:225], 0, s[16:17]
	s_mov_b32 m0, s50
	s_nop 0
	global_load_lds_dwordx4 v[182:183], off
	v_lshl_add_u64 v[182:183], v[226:227], 0, s[16:17]
	s_mov_b32 m0, s51
	s_nop 0
	global_load_lds_dwordx4 v[182:183], off
	s_waitcnt vmcnt(8)
	s_waitcnt lgkmcnt(0)
	s_barrier
	s_setprio 1
	s_waitcnt lgkmcnt(0)
	v_mfma_f32_16x16x32_bf16 v[62:65], v[148:151], v[190:193], v[62:65]
	v_mfma_f32_16x16x32_bf16 v[58:61], v[162:165], v[190:193], v[58:61]
	v_mfma_f32_16x16x32_bf16 v[46:49], v[148:151], v[198:201], v[46:49]
	v_mfma_f32_16x16x32_bf16 v[42:45], v[162:165], v[198:201], v[42:45]
	v_mfma_f32_16x16x32_bf16 v[30:33], v[148:151], v[206:209], v[30:33]
	v_mfma_f32_16x16x32_bf16 v[26:29], v[162:165], v[206:209], v[26:29]
	v_mfma_f32_16x16x32_bf16 v[14:17], v[148:151], v[214:217], v[14:17]
	v_mfma_f32_16x16x32_bf16 v[10:13], v[162:165], v[214:217], v[10:13]
	v_mfma_f32_16x16x32_bf16 v[62:65], v[158:161], v[194:197], v[62:65]
	v_mfma_f32_16x16x32_bf16 v[58:61], v[166:169], v[194:197], v[58:61]
	v_mfma_f32_16x16x32_bf16 v[46:49], v[158:161], v[202:205], v[46:49]
	v_mfma_f32_16x16x32_bf16 v[42:45], v[166:169], v[202:205], v[42:45]
	v_mfma_f32_16x16x32_bf16 v[30:33], v[158:161], v[210:213], v[30:33]
	v_mfma_f32_16x16x32_bf16 v[26:29], v[166:169], v[210:213], v[26:29]
	v_mfma_f32_16x16x32_bf16 v[14:17], v[158:161], v[218:221], v[14:17]
	v_mfma_f32_16x16x32_bf16 v[10:13], v[166:169], v[218:221], v[10:13]
	s_setprio 0
	s_setprio 1
	v_mfma_f32_16x16x32_bf16 v[54:57], v[170:173], v[190:193], v[54:57]
	v_mfma_f32_16x16x32_bf16 v[50:53], v[178:181], v[190:193], v[50:53]
	v_mfma_f32_16x16x32_bf16 v[38:41], v[170:173], v[198:201], v[38:41]
	v_mfma_f32_16x16x32_bf16 v[34:37], v[178:181], v[198:201], v[34:37]
	v_mfma_f32_16x16x32_bf16 v[22:25], v[170:173], v[206:209], v[22:25]
	v_mfma_f32_16x16x32_bf16 v[18:21], v[178:181], v[206:209], v[18:21]
	v_mfma_f32_16x16x32_bf16 v[6:9], v[170:173], v[214:217], v[6:9]
	v_mfma_f32_16x16x32_bf16 v[2:5], v[178:181], v[214:217], v[2:5]
	v_mfma_f32_16x16x32_bf16 v[54:57], v[174:177], v[194:197], v[54:57]
	v_mfma_f32_16x16x32_bf16 v[50:53], v[186:189], v[194:197], v[50:53]
	v_mfma_f32_16x16x32_bf16 v[38:41], v[174:177], v[202:205], v[38:41]
	v_mfma_f32_16x16x32_bf16 v[34:37], v[186:189], v[202:205], v[34:37]
	v_mfma_f32_16x16x32_bf16 v[22:25], v[174:177], v[210:213], v[22:25]
	v_mfma_f32_16x16x32_bf16 v[18:21], v[186:189], v[210:213], v[18:21]
	v_mfma_f32_16x16x32_bf16 v[6:9], v[174:177], v[218:221], v[6:9]
	v_mfma_f32_16x16x32_bf16 v[2:5], v[186:189], v[218:221], v[2:5]
	s_setprio 0
	s_barrier
	s_add_i32 s62, s62, 2
	s_add_u32 s36, s36, 0x100
	s_addc_u32 s37, s37, 0
	s_add_u32 s60, s60, 0x100
	s_addc_u32 s61, s61, 0
	s_cmp_gt_u32 s62, 41

;     DI bool next(int i, Unit& u) const { if (i > 0 || c >= 64) return false; u.pm = c & 31; u.pn = 0; u.src = c >> 5; return true; }
; #define PG8_STAGE(bufoff, gbase, voff) do { _Pragma("unroll") for (int _i = 0; _i < 2; ++_i) \
;         __builtin_amdgcn_global_load_lds((const unsigned*)((const char*)(gbase) + (voff)[_i]), (LAS unsigned*)(lds + (bufoff) + ldsw + _i * 8192), 16, 0, 0); } while (0)
; #define PG8_LDA(dst, b, h) do { _Pragma("unroll") for (int m = 0; m < 4; ++m) _Pragma("unroll") for (int k = 0; k < 2; ++k) dst[m][k] = *(const LAS bf16x8*)(lds + PG8_SA(b, h) + aoff + m * 2048 + k * 1024); } while (0)
; #define PG8_LDB(dst, b, h) do { _Pragma("unroll") for (int n = 0; n < 2; ++n) _Pragma("unroll") for (int k = 0; k < 2; ++k) dst[n][k] = *(const LAS bf16x8*)(lds + PG8_SB(b, h) + boff + n * 2048 + k * 1024); } while (0)
; #define PG8_WAIT_V(n) asm volatile("s_waitcnt vmcnt(" #n ")" ::: "memory")
; #define PG8_WAIT_L(n) asm volatile("s_waitcnt lgkmcnt(" #n ")" ::: "memory")
; #define PG8_BAR __builtin_amdgcn_s_barrier()
; #define PG8_SCHED __builtin_amdgcn_sched_barrier(0)
; template <class Epi, class Sched>
; DI void gemm_phase(LAS unsigned char* lds, const Gemm g, const Sched& S, const Epi& E) {
;     ...
;         const bool has_next = S.next(ui + 1, nxt);
;         E.pre(pre, cur, wr, fr);
;         const char* nA = has_next ? (const char*)(nxt.src ? g.A1 : g.A0) + (size_t)nxt.pm * tstepA : cA; const char* nB = has_next ? (const char*)(nxt.src ? g.B1 : g.B0) + (size_t)nxt.pn * tstepB : cB;
;         for (int t = 0; t < nt; t += 2) {
;             const bool last = (t == nt - 2);
;             const char* a1 = cA + (size_t)(t + 1) * kstep;
;             const char* a2 = last ? nA : cA + (size_t)(t + 2) * kstep; const char* b2 = last ? nB : cB + (size_t)(t + 2) * kstep;
;             const char* a3 = a2 + kstep; const char* b3 = b2 + kstep;
;             PG8_LDB(B0, 0, 0); PG8_LDB(B1, 0, 1); PG8_SCHED; PG8_LDA(At, 0, 0); PG8_STAGE(PG8_SA(1, 1), a1 + hstepA, voffA);
;             PG8_WAIT_V(8); PG8_WAIT_L(0); PG8_BAR; PG8_MMA(0, 0, At, B0); PG8_MMA(0, 1, At, B1); PG8_BAR; PG8_SCHED;
;             PG8_LDA(At, 0, 1); PG8_STAGE(PG8_SB(0, 0), b2, voffB); PG8_STAGE(PG8_SB(0, 1), b2 + hstepB, voffB); PG8_STAGE(PG8_SA(0, 0), a2, voffA);
;             PG8_WAIT_V(8); PG8_WAIT_L(0); PG8_BAR; PG8_MMA(1, 0, At, B0); PG8_MMA(1, 1, At, B1); PG8_BAR; PG8_SCHED;
.LBB0_380:
	s_lshl_b32 s28, s10, 8
	s_add_i32 s28, s28, s85
	v_or_b32_e32 v170, s28, v147
	v_ashrrev_i32_e32 v171, 31, v170
	v_add_u32_e32 v136, 0x80, v170
	v_add_u32_e32 v134, 0x90, v170
	v_add_u32_e32 v132, 0xa0, v170
	v_add_u32_e32 v130, 0xb0, v170
	v_lshl_add_u64 v[2:3], v[170:171], 2, s[20:21]
	v_ashrrev_i32_e32 v137, 31, v136
	v_ashrrev_i32_e32 v135, 31, v134
	v_ashrrev_i32_e32 v133, 31, v132
	v_ashrrev_i32_e32 v131, 31, v130
	v_lshl_add_u64 v[4:5], v[136:137], 2, s[20:21]
	v_lshl_add_u64 v[6:7], v[134:135], 2, s[20:21]
	v_lshl_add_u64 v[8:9], v[132:133], 2, s[20:21]
	v_lshl_add_u64 v[10:11], v[130:131], 2, s[20:21]
	global_load_dword v174, v[2:3], off
	global_load_dword v197, v[2:3], off offset:64
	global_load_dword v196, v[2:3], off offset:128
	global_load_dword v195, v[2:3], off offset:192
	global_load_dword v194, v[4:5], off
	global_load_dword v193, v[6:7], off
	global_load_dword v192, v[8:9], off
	global_load_dword v191, v[10:11], off
	s_ashr_i32 s59, s58, 31
	s_lshl_b64 s[10:11], s[58:59], 19
	s_add_u32 s60, s30, s10
	s_addc_u32 s61, s31, s11
	s_and_b64 s[10:11], s[8:9], exec
	s_cselect_b32 s13, s61, s67
	s_cselect_b32 s29, s60, s66
	s_ashr_i32 s57, s56, 31
	s_lshl_b64 s[10:11], s[56:57], 19
	s_add_u32 s62, s75, s10
	s_addc_u32 s63, s76, s11
	s_and_b64 s[10:11], s[8:9], exec
	s_cselect_b32 s36, s63, s65
	s_cselect_b32 s57, s62, s64
	s_add_u32 s10, s66, 0x40080
	s_addc_u32 s11, s67, 0
	s_add_u32 s59, s64, 0x100
	s_addc_u32 s68, s65, 0
	s_mov_b32 s69, -2
	s_waitcnt lgkmcnt(0)
	ds_read_b128 v[138:141], v188
	ds_read_b128 v[142:145], v188 offset:1024
	ds_read_b128 v[176:179], v188 offset:2048
	ds_read_b128 v[198:201], v188 offset:3072
	ds_read_b128 v[202:205], v189
	ds_read_b128 v[206:209], v189 offset:1024
	ds_read_b128 v[210:213], v189 offset:2048
	ds_read_b128 v[214:217], v189 offset:3072
	s_add_u32 s64, s10, 0xfffc0080
	s_addc_u32 s65, s11, -1
	s_cmp_eq_u32 s69, 12
	s_cselect_b32 s67, s13, s65
	s_cselect_b32 s66, s29, s64
	s_cselect_b32 s65, s36, s68
	s_cselect_b32 s64, s57, s59
	v_lshl_add_u64 v[172:173], s[10:11], 0, v[162:163]
	s_add_i32 m0, s79, 0xc000
	ds_read_b128 v[218:221], v186
	ds_read_b128 v[222:225], v186 offset:1024
	ds_read_b128 v[226:229], v186 offset:2048
	ds_read_b128 v[230:233], v186 offset:3072
	ds_read_b128 v[234:237], v186 offset:4096
	ds_read_b128 v[238:241], v186 offset:5120
	ds_read_b128 v[242:245], v186 offset:6144
	ds_read_b128 v[246:249], v186 offset:7168
	global_load_lds_dwordx4 v[172:173], off
	v_lshl_add_u64 v[172:173], s[10:11], 0, v[164:165]
	s_add_i32 m0, s79, 0xe000
	s_nop 0
	global_load_lds_dwordx4 v[172:173], off
	s_waitcnt vmcnt(8)
	s_waitcnt lgkmcnt(0)
	s_barrier
	s_setprio 1
	s_waitcnt lgkmcnt(0)
	v_mfma_f32_16x16x32_bf16 v[126:129], v[138:141], v[218:221], 0
	v_mfma_f32_16x16x32_bf16 v[122:125], v[176:179], v[218:221], 0
	v_mfma_f32_16x16x32_bf16 v[110:113], v[138:141], v[226:229], 0
	v_mfma_f32_16x16x32_bf16 v[106:109], v[176:179], v[226:229], 0
	v_mfma_f32_16x16x32_bf16 v[94:97], v[138:141], v[234:237], 0
	v_mfma_f32_16x16x32_bf16 v[90:93], v[176:179], v[234:237], 0
	v_mfma_f32_16x16x32_bf16 v[78:81], v[138:141], v[242:245], 0
	v_mfma_f32_16x16x32_bf16 v[74:77], v[176:179], v[242:245], 0
	v_mfma_f32_16x16x32_bf16 v[126:129], v[142:145], v[222:225], v[126:129]
	v_mfma_f32_16x16x32_bf16 v[122:125], v[198:201], v[222:225], v[122:125]
	v_mfma_f32_16x16x32_bf16 v[110:113], v[142:145], v[230:233], v[110:113]
	v_mfma_f32_16x16x32_bf16 v[106:109], v[198:201], v[230:233], v[106:109]
	v_mfma_f32_16x16x32_bf16 v[94:97], v[142:145], v[238:241], v[94:97]
	v_mfma_f32_16x16x32_bf16 v[90:93], v[198:201], v[238:241], v[90:93]
	v_mfma_f32_16x16x32_bf16 v[78:81], v[142:145], v[246:249], v[78:81]
	v_mfma_f32_16x16x32_bf16 v[74:77], v[198:201], v[246:249], v[74:77]
	s_setprio 0
	s_setprio 1
	v_mfma_f32_16x16x32_bf16 v[118:121], v[202:205], v[218:221], 0
	v_mfma_f32_16x16x32_bf16 v[114:117], v[210:213], v[218:221], 0
	v_mfma_f32_16x16x32_bf16 v[102:105], v[202:205], v[226:229], 0
	v_mfma_f32_16x16x32_bf16 v[98:101], v[210:213], v[226:229], 0
	v_mfma_f32_16x16x32_bf16 v[86:89], v[202:205], v[234:237], 0
	v_mfma_f32_16x16x32_bf16 v[82:85], v[210:213], v[234:237], 0
	v_mfma_f32_16x16x32_bf16 v[70:73], v[202:205], v[242:245], 0
	v_mfma_f32_16x16x32_bf16 v[66:69], v[210:213], v[242:245], 0
	v_mfma_f32_16x16x32_bf16 v[118:121], v[206:209], v[222:225], v[118:121]
	v_mfma_f32_16x16x32_bf16 v[114:117], v[214:217], v[222:225], v[114:117]
	v_mfma_f32_16x16x32_bf16 v[102:105], v[206:209], v[230:233], v[102:105]
	v_mfma_f32_16x16x32_bf16 v[98:101], v[214:217], v[230:233], v[98:101]
	v_mfma_f32_16x16x32_bf16 v[86:89], v[206:209], v[238:241], v[86:89]
	v_mfma_f32_16x16x32_bf16 v[82:85], v[214:217], v[238:241], v[82:85]
	v_mfma_f32_16x16x32_bf16 v[70:73], v[206:209], v[246:249], v[70:73]
	v_mfma_f32_16x16x32_bf16 v[66:69], v[214:217], v[246:249], v[66:69]
	s_setprio 0
	s_barrier
	s_add_i32 s70, s94, s78
	v_lshl_add_u64 v[172:173], s[64:65], 0, v[150:151]
	s_mov_b32 m0, s70
	ds_read_b128 v[218:221], v186 offset:16384
	ds_read_b128 v[222:225], v186 offset:17408
	ds_read_b128 v[226:229], v186 offset:18432
	ds_read_b128 v[230:233], v186 offset:19456
	ds_read_b128 v[234:237], v186 offset:20480
	ds_read_b128 v[238:241], v186 offset:21504
	ds_read_b128 v[242:245], v186 offset:22528
	ds_read_b128 v[246:249], v186 offset:23552
	global_load_lds_dwordx4 v[172:173], off
	s_add_i32 m0, s70, 0x2000
	s_add_u32 s70, s64, 0x40000
	v_lshl_add_u64 v[180:181], s[64:65], 0, v[154:155]
	s_addc_u32 s71, s65, 0
	s_add_i32 s72, s95, s78
	global_load_lds_dwordx4 v[180:181], off
	v_lshl_add_u64 v[250:251], s[70:71], 0, v[150:151]
	s_mov_b32 m0, s72
	v_lshl_add_u64 v[252:253], s[66:67], 0, v[152:153]
	global_load_lds_dwordx4 v[250:251], off
	v_lshl_add_u64 v[250:251], s[70:71], 0, v[154:155]
	s_add_i32 m0, s72, 0x2000
	s_nop 0
	global_load_lds_dwordx4 v[250:251], off
	v_lshl_add_u64 v[250:251], s[66:67], 0, v[148:149]
	s_mov_b32 m0, s79
	s_nop 0
	global_load_lds_dwordx4 v[250:251], off
	s_mov_b32 m0, s80
	s_nop 0
	global_load_lds_dwordx4 v[252:253], off
	s_waitcnt vmcnt(8)
	s_waitcnt lgkmcnt(0)
	s_barrier
; #define PG8_STAGE(bufoff, gbase, voff) do { _Pragma("unroll") for (int _i = 0; _i < 2; ++_i) \
;         __builtin_amdgcn_global_load_lds((const unsigned*)((const char*)(gbase) + (voff)[_i]), (LAS unsigned*)(lds + (bufoff) + ldsw + _i * 8192), 16, 0, 0); } while (0)
; #define PG8_LDA(dst, b, h) do { _Pragma("unroll") for (int m = 0; m < 4; ++m) _Pragma("unroll") for (int k = 0; k < 2; ++k) dst[m][k] = *(const LAS bf16x8*)(lds + PG8_SA(b, h) + aoff + m * 2048 + k * 1024); } while (0)
; #define PG8_LDB(dst, b, h) do { _Pragma("unroll") for (int n = 0; n < 2; ++n) _Pragma("unroll") for (int k = 0; k < 2; ++k) dst[n][k] = *(const LAS bf16x8*)(lds + PG8_SB(b, h) + boff + n * 2048 + k * 1024); } while (0)
; #define PG8_MMA(ai, bj, At, Bt) do { __builtin_amdgcn_s_setprio(1); _Pragma("unroll") for (int m = 0; m < 4; ++m) _Pragma("unroll") for (int n = 0; n < 2; ++n) _Pragma("unroll") for (int k = 0; k < 2; ++k) \
;         acc[ai][bj][m][n] = __builtin_amdgcn_mfma_f32_16x16x32_bf16(Bt[n][k], At[m][k], acc[ai][bj][m][n], 0, 0, 0); __builtin_amdgcn_s_setprio(0); } while (0)
; #define PG8_WAIT_V(n) asm volatile("s_waitcnt vmcnt(" #n ")" ::: "memory")
; #define PG8_WAIT_L(n) asm volatile("s_waitcnt lgkmcnt(" #n ")" ::: "memory")
; #define PG8_BAR __builtin_amdgcn_s_barrier()
; #define PG8_SCHED __builtin_amdgcn_sched_barrier(0)
; template <class Epi, class Sched>
; DI void gemm_phase(LAS unsigned char* lds, const Gemm g, const Sched& S, const Epi& E) {
;     ...
;             PG8_WAIT_V(8); PG8_WAIT_L(0); PG8_BAR; PG8_MMA(1, 0, At, B0); PG8_MMA(1, 1, At, B1); PG8_BAR; PG8_SCHED;
;             PG8_LDB(B0, 1, 0); PG8_LDB(B1, 1, 1); PG8_SCHED; PG8_LDA(At, 1, 0); PG8_STAGE(PG8_SA(0, 1), a2 + hstepA, voffA);
;             PG8_WAIT_V(8); PG8_WAIT_L(0); PG8_BAR; PG8_MMA(0, 0, At, B0); PG8_MMA(0, 1, At, B1); PG8_BAR; PG8_SCHED;
	s_setprio 1
	s_waitcnt lgkmcnt(0)
	v_mfma_f32_16x16x32_bf16 v[62:65], v[138:141], v[218:221], 0
	v_mfma_f32_16x16x32_bf16 v[58:61], v[176:179], v[218:221], 0
	v_mfma_f32_16x16x32_bf16 v[46:49], v[138:141], v[226:229], 0
	v_mfma_f32_16x16x32_bf16 v[42:45], v[176:179], v[226:229], 0
	v_mfma_f32_16x16x32_bf16 v[30:33], v[138:141], v[234:237], 0
	v_mfma_f32_16x16x32_bf16 v[26:29], v[176:179], v[234:237], 0
	v_mfma_f32_16x16x32_bf16 v[14:17], v[138:141], v[242:245], 0
	v_mfma_f32_16x16x32_bf16 v[10:13], v[176:179], v[242:245], 0
	v_mfma_f32_16x16x32_bf16 v[62:65], v[142:145], v[222:225], v[62:65]
	v_mfma_f32_16x16x32_bf16 v[58:61], v[198:201], v[222:225], v[58:61]
	v_mfma_f32_16x16x32_bf16 v[46:49], v[142:145], v[230:233], v[46:49]
	v_mfma_f32_16x16x32_bf16 v[42:45], v[198:201], v[230:233], v[42:45]
	v_mfma_f32_16x16x32_bf16 v[30:33], v[142:145], v[238:241], v[30:33]
	v_mfma_f32_16x16x32_bf16 v[26:29], v[198:201], v[238:241], v[26:29]
	v_mfma_f32_16x16x32_bf16 v[14:17], v[142:145], v[246:249], v[14:17]
	v_mfma_f32_16x16x32_bf16 v[10:13], v[198:201], v[246:249], v[10:13]
	s_setprio 0
	s_setprio 1
	v_mfma_f32_16x16x32_bf16 v[54:57], v[202:205], v[218:221], 0
	v_mfma_f32_16x16x32_bf16 v[50:53], v[210:213], v[218:221], 0
	v_mfma_f32_16x16x32_bf16 v[38:41], v[202:205], v[226:229], 0
	v_mfma_f32_16x16x32_bf16 v[34:37], v[210:213], v[226:229], 0
	v_mfma_f32_16x16x32_bf16 v[22:25], v[202:205], v[234:237], 0
	v_mfma_f32_16x16x32_bf16 v[18:21], v[210:213], v[234:237], 0
	v_mfma_f32_16x16x32_bf16 v[6:9], v[202:205], v[242:245], 0
	v_mfma_f32_16x16x32_bf16 v[2:5], v[210:213], v[242:245], 0
	v_mfma_f32_16x16x32_bf16 v[54:57], v[206:209], v[222:225], v[54:57]
	v_mfma_f32_16x16x32_bf16 v[50:53], v[214:217], v[222:225], v[50:53]
	v_mfma_f32_16x16x32_bf16 v[38:41], v[206:209], v[230:233], v[38:41]
	v_mfma_f32_16x16x32_bf16 v[34:37], v[214:217], v[230:233], v[34:37]
	v_mfma_f32_16x16x32_bf16 v[22:25], v[206:209], v[238:241], v[22:25]
	v_mfma_f32_16x16x32_bf16 v[18:21], v[214:217], v[238:241], v[18:21]
	v_mfma_f32_16x16x32_bf16 v[6:9], v[206:209], v[246:249], v[6:9]
	v_mfma_f32_16x16x32_bf16 v[2:5], v[214:217], v[246:249], v[2:5]
	s_setprio 0
	s_barrier
	s_add_i32 s70, 0, 0x18000
	v_add_u32_e32 v156, s70, v159
	s_add_i32 s71, 0, 0x1c000
	ds_read_b128 v[138:141], v156
	ds_read_b128 v[142:145], v156 offset:1024
	ds_read_b128 v[176:179], v156 offset:2048
	ds_read_b128 v[198:201], v156 offset:3072
	v_add_u32_e32 v156, s71, v159
	ds_read_b128 v[202:205], v156
	ds_read_b128 v[206:209], v156 offset:1024
	ds_read_b128 v[210:213], v156 offset:2048
	ds_read_b128 v[214:217], v156 offset:3072
	s_add_u32 s66, s66, 0x40000
	s_addc_u32 s67, s67, 0
	s_mov_b32 m0, s81
	v_lshl_add_u64 v[254:255], s[66:67], 0, v[148:149]
	ds_read_b128 v[218:221], v186 offset:32768
	ds_read_b128 v[222:225], v186 offset:33792
	ds_read_b128 v[226:229], v186 offset:34816
	ds_read_b128 v[230:233], v186 offset:35840
	ds_read_b128 v[234:237], v186 offset:36864
	ds_read_b128 v[238:241], v186 offset:37888
	ds_read_b128 v[242:245], v186 offset:38912
	ds_read_b128 v[246:249], v186 offset:39936
	global_load_lds_dwordx4 v[254:255], off
	v_lshl_add_u64 v[254:255], s[66:67], 0, v[152:153]
	s_mov_b32 m0, s82
	s_nop 0
	global_load_lds_dwordx4 v[254:255], off
	s_waitcnt vmcnt(8)
	s_waitcnt lgkmcnt(0)
	s_barrier
	s_setprio 1
	s_waitcnt lgkmcnt(0)
	v_mfma_f32_16x16x32_bf16 v[126:129], v[138:141], v[218:221], v[126:129]
	v_mfma_f32_16x16x32_bf16 v[122:125], v[176:179], v[218:221], v[122:125]
	v_mfma_f32_16x16x32_bf16 v[110:113], v[138:141], v[226:229], v[110:113]
	v_mfma_f32_16x16x32_bf16 v[106:109], v[176:179], v[226:229], v[106:109]
	v_mfma_f32_16x16x32_bf16 v[94:97], v[138:141], v[234:237], v[94:97]
	v_mfma_f32_16x16x32_bf16 v[90:93], v[176:179], v[234:237], v[90:93]
	v_mfma_f32_16x16x32_bf16 v[78:81], v[138:141], v[242:245], v[78:81]
	v_mfma_f32_16x16x32_bf16 v[74:77], v[176:179], v[242:245], v[74:77]
	v_mfma_f32_16x16x32_bf16 v[126:129], v[142:145], v[222:225], v[126:129]
	v_mfma_f32_16x16x32_bf16 v[122:125], v[198:201], v[222:225], v[122:125]
	v_mfma_f32_16x16x32_bf16 v[110:113], v[142:145], v[230:233], v[110:113]
	v_mfma_f32_16x16x32_bf16 v[106:109], v[198:201], v[230:233], v[106:109]
	v_mfma_f32_16x16x32_bf16 v[94:97], v[142:145], v[238:241], v[94:97]
	v_mfma_f32_16x16x32_bf16 v[90:93], v[198:201], v[238:241], v[90:93]
	v_mfma_f32_16x16x32_bf16 v[78:81], v[142:145], v[246:249], v[78:81]
	v_mfma_f32_16x16x32_bf16 v[74:77], v[198:201], v[246:249], v[74:77]
	s_setprio 0
	s_setprio 1
	v_mfma_f32_16x16x32_bf16 v[118:121], v[202:205], v[218:221], v[118:121]
	v_mfma_f32_16x16x32_bf16 v[114:117], v[210:213], v[218:221], v[114:117]
	v_mfma_f32_16x16x32_bf16 v[102:105], v[202:205], v[226:229], v[102:105]
	v_mfma_f32_16x16x32_bf16 v[98:101], v[210:213], v[226:229], v[98:101]
	v_mfma_f32_16x16x32_bf16 v[86:89], v[202:205], v[234:237], v[86:89]
	v_mfma_f32_16x16x32_bf16 v[82:85], v[210:213], v[234:237], v[82:85]
	v_mfma_f32_16x16x32_bf16 v[70:73], v[202:205], v[242:245], v[70:73]
	v_mfma_f32_16x16x32_bf16 v[66:69], v[210:213], v[242:245], v[66:69]
	v_mfma_f32_16x16x32_bf16 v[118:121], v[206:209], v[222:225], v[118:121]
	v_mfma_f32_16x16x32_bf16 v[114:117], v[214:217], v[222:225], v[114:117]
	v_mfma_f32_16x16x32_bf16 v[102:105], v[206:209], v[230:233], v[102:105]
	v_mfma_f32_16x16x32_bf16 v[98:101], v[214:217], v[230:233], v[98:101]
	v_mfma_f32_16x16x32_bf16 v[86:89], v[206:209], v[238:241], v[86:89]
	v_mfma_f32_16x16x32_bf16 v[82:85], v[214:217], v[238:241], v[82:85]
	v_mfma_f32_16x16x32_bf16 v[70:73], v[206:209], v[246:249], v[70:73]
	v_mfma_f32_16x16x32_bf16 v[66:69], v[214:217], v[246:249], v[66:69]
	s_setprio 0
	s_barrier
; #define PG8_STAGE(bufoff, gbase, voff) do { _Pragma("unroll") for (int _i = 0; _i < 2; ++_i) \
;         __builtin_amdgcn_global_load_lds((const unsigned*)((const char*)(gbase) + (voff)[_i]), (LAS unsigned*)(lds + (bufoff) + ldsw + _i * 8192), 16, 0, 0); } while (0)
; #define PG8_LDA(dst, b, h) do { _Pragma("unroll") for (int m = 0; m < 4; ++m) _Pragma("unroll") for (int k = 0; k < 2; ++k) dst[m][k] = *(const LAS bf16x8*)(lds + PG8_SA(b, h) + aoff + m * 2048 + k * 1024); } while (0)
; #define PG8_MMA(ai, bj, At, Bt) do { __builtin_amdgcn_s_setprio(1); _Pragma("unroll") for (int m = 0; m < 4; ++m) _Pragma("unroll") for (int n = 0; n < 2; ++n) _Pragma("unroll") for (int k = 0; k < 2; ++k) \
;         acc[ai][bj][m][n] = __builtin_amdgcn_mfma_f32_16x16x32_bf16(Bt[n][k], At[m][k], acc[ai][bj][m][n], 0, 0, 0); __builtin_amdgcn_s_setprio(0); } while (0)
; #define PG8_WAIT_V(n) asm volatile("s_waitcnt vmcnt(" #n ")" ::: "memory")
; #define PG8_WAIT_L(n) asm volatile("s_waitcnt lgkmcnt(" #n ")" ::: "memory")
; #define PG8_BAR __builtin_amdgcn_s_barrier()
; #define PG8_SCHED __builtin_amdgcn_sched_barrier(0)
; template <class Epi, class Sched>
; DI void gemm_phase(LAS unsigned char* lds, const Gemm g, const Sched& S, const Epi& E) {
;     ...
;             PG8_WAIT_V(8); PG8_WAIT_L(0); PG8_BAR; PG8_MMA(0, 0, At, B0); PG8_MMA(0, 1, At, B1); PG8_BAR; PG8_SCHED;
;             PG8_LDA(At, 1, 1); PG8_STAGE(PG8_SB(1, 0), b3, voffB); PG8_STAGE(PG8_SB(1, 1), b3 + hstepB, voffB); PG8_STAGE(PG8_SA(1, 0), a3, voffA);
;             PG8_WAIT_V(8); PG8_WAIT_L(0); PG8_BAR; PG8_MMA(1, 0, At, B0); PG8_MMA(1, 1, At, B1); PG8_BAR; PG8_SCHED;
;         }
	s_add_i32 s66, s70, s78
	v_lshl_add_u64 v[172:173], v[172:173], 0, s[50:51]
	s_mov_b32 m0, s66
	ds_read_b128 v[218:221], v186 offset:49152
	ds_read_b128 v[222:225], v186 offset:50176
	ds_read_b128 v[226:229], v186 offset:51200
	ds_read_b128 v[230:233], v186 offset:52224
	ds_read_b128 v[234:237], v186 offset:53248
	ds_read_b128 v[238:241], v186 offset:54272
	ds_read_b128 v[242:245], v186 offset:55296
	ds_read_b128 v[246:249], v186 offset:56320
	global_load_lds_dwordx4 v[172:173], off
	s_add_i32 m0, s66, 0x2000
	s_add_u32 s64, s64, 0x40080
	v_lshl_add_u64 v[172:173], v[180:181], 0, s[50:51]
	s_addc_u32 s65, s65, 0
	s_add_i32 s66, s71, s78
	global_load_lds_dwordx4 v[172:173], off
	v_lshl_add_u64 v[172:173], s[64:65], 0, v[150:151]
	s_mov_b32 m0, s66
	s_nop 0
	global_load_lds_dwordx4 v[172:173], off
	v_lshl_add_u64 v[172:173], s[64:65], 0, v[154:155]
	s_add_i32 m0, s66, 0x2000
	s_nop 0
	global_load_lds_dwordx4 v[172:173], off
	v_lshl_add_u64 v[172:173], v[250:251], 0, s[50:51]
	s_mov_b32 m0, s86
	s_nop 0
	global_load_lds_dwordx4 v[172:173], off
	v_lshl_add_u64 v[172:173], v[252:253], 0, s[50:51]
	s_mov_b32 m0, s87
	s_nop 0
	global_load_lds_dwordx4 v[172:173], off
	s_waitcnt vmcnt(8)
	s_waitcnt lgkmcnt(0)
	s_barrier
	s_setprio 1
	s_waitcnt lgkmcnt(0)
	v_mfma_f32_16x16x32_bf16 v[62:65], v[138:141], v[218:221], v[62:65]
	v_mfma_f32_16x16x32_bf16 v[58:61], v[176:179], v[218:221], v[58:61]
	v_mfma_f32_16x16x32_bf16 v[46:49], v[138:141], v[226:229], v[46:49]
	v_mfma_f32_16x16x32_bf16 v[42:45], v[176:179], v[226:229], v[42:45]
	v_mfma_f32_16x16x32_bf16 v[30:33], v[138:141], v[234:237], v[30:33]
	v_mfma_f32_16x16x32_bf16 v[26:29], v[176:179], v[234:237], v[26:29]
	v_mfma_f32_16x16x32_bf16 v[14:17], v[138:141], v[242:245], v[14:17]
	v_mfma_f32_16x16x32_bf16 v[10:13], v[176:179], v[242:245], v[10:13]
	v_mfma_f32_16x16x32_bf16 v[62:65], v[142:145], v[222:225], v[62:65]
	v_mfma_f32_16x16x32_bf16 v[58:61], v[198:201], v[222:225], v[58:61]
	v_mfma_f32_16x16x32_bf16 v[46:49], v[142:145], v[230:233], v[46:49]
	v_mfma_f32_16x16x32_bf16 v[42:45], v[198:201], v[230:233], v[42:45]
	v_mfma_f32_16x16x32_bf16 v[30:33], v[142:145], v[238:241], v[30:33]
	v_mfma_f32_16x16x32_bf16 v[26:29], v[198:201], v[238:241], v[26:29]
	v_mfma_f32_16x16x32_bf16 v[14:17], v[142:145], v[246:249], v[14:17]
	v_mfma_f32_16x16x32_bf16 v[10:13], v[198:201], v[246:249], v[10:13]
	s_setprio 0
	s_setprio 1
	v_mfma_f32_16x16x32_bf16 v[54:57], v[202:205], v[218:221], v[54:57]
	v_mfma_f32_16x16x32_bf16 v[50:53], v[210:213], v[218:221], v[50:53]
	v_mfma_f32_16x16x32_bf16 v[38:41], v[202:205], v[226:229], v[38:41]
	v_mfma_f32_16x16x32_bf16 v[34:37], v[210:213], v[226:229], v[34:37]
	v_mfma_f32_16x16x32_bf16 v[22:25], v[202:205], v[234:237], v[22:25]
	v_mfma_f32_16x16x32_bf16 v[18:21], v[210:213], v[234:237], v[18:21]
	v_mfma_f32_16x16x32_bf16 v[6:9], v[202:205], v[242:245], v[6:9]
	v_mfma_f32_16x16x32_bf16 v[2:5], v[210:213], v[242:245], v[2:5]
	v_mfma_f32_16x16x32_bf16 v[54:57], v[206:209], v[222:225], v[54:57]
	v_mfma_f32_16x16x32_bf16 v[50:53], v[214:217], v[222:225], v[50:53]
	v_mfma_f32_16x16x32_bf16 v[38:41], v[206:209], v[230:233], v[38:41]
	v_mfma_f32_16x16x32_bf16 v[34:37], v[214:217], v[230:233], v[34:37]
	v_mfma_f32_16x16x32_bf16 v[22:25], v[206:209], v[238:241], v[22:25]
	v_mfma_f32_16x16x32_bf16 v[18:21], v[214:217], v[238:241], v[18:21]
	v_mfma_f32_16x16x32_bf16 v[6:9], v[206:209], v[246:249], v[6:9]
	v_mfma_f32_16x16x32_bf16 v[2:5], v[214:217], v[246:249], v[2:5]
	s_setprio 0
	s_barrier
	s_add_i32 s69, s69, 2
	s_add_u32 s10, s10, 0x100
	s_addc_u32 s11, s11, 0
	s_add_u32 s59, s59, 0x100
	s_addc_u32 s68, s68, 0
	s_cmp_gt_u32 s69, 13

; #define PG8_STAGE(bufoff, gbase, voff) do { _Pragma("unroll") for (int _i = 0; _i < 2; ++_i) \
;         __builtin_amdgcn_global_load_lds((const unsigned*)((const char*)(gbase) + (voff)[_i]), (LAS unsigned*)(lds + (bufoff) + ldsw + _i * 8192), 16, 0, 0); } while (0)
; #define PG8_LDA(dst, b, h) do { _Pragma("unroll") for (int m = 0; m < 4; ++m) _Pragma("unroll") for (int k = 0; k < 2; ++k) dst[m][k] = *(const LAS bf16x8*)(lds + PG8_SA(b, h) + aoff + m * 2048 + k * 1024); } while (0)
; #define PG8_LDB(dst, b, h) do { _Pragma("unroll") for (int n = 0; n < 2; ++n) _Pragma("unroll") for (int k = 0; k < 2; ++k) dst[n][k] = *(const LAS bf16x8*)(lds + PG8_SB(b, h) + boff + n * 2048 + k * 1024); } while (0)
; #define PG8_MMA(ai, bj, At, Bt) do { __builtin_amdgcn_s_setprio(1); _Pragma("unroll") for (int m = 0; m < 4; ++m) _Pragma("unroll") for (int n = 0; n < 2; ++n) _Pragma("unroll") for (int k = 0; k < 2; ++k) \
;         acc[ai][bj][m][n] = __builtin_amdgcn_mfma_f32_16x16x32_bf16(Bt[n][k], At[m][k], acc[ai][bj][m][n], 0, 0, 0); __builtin_amdgcn_s_setprio(0); } while (0)
; #define PG8_WAIT_V(n) asm volatile("s_waitcnt vmcnt(" #n ")" ::: "memory")
; template <class Epi, class Sched>
; DI void gemm_phase(LAS unsigned char* lds, const Gemm g, const Sched& S, const Epi& E) {
;     ...
;         const char* nA = has_next ? (const char*)(nxt.src ? g.A1 : g.A0) + (size_t)nxt.pm * tstepA : cA; const char* nB = has_next ? (const char*)(nxt.src ? g.B1 : g.B0) + (size_t)nxt.pn * tstepB : cB;
;         for (int t = 0; t < nt; t += 2) {
;             const bool last = (t == nt - 2);
;             const char* a1 = cA + (size_t)(t + 1) * kstep;
;             const char* a2 = last ? nA : cA + (size_t)(t + 2) * kstep; const char* b2 = last ? nB : cB + (size_t)(t + 2) * kstep;
;             const char* a3 = a2 + kstep; const char* b3 = b2 + kstep;
;             PG8_LDB(B0, 0, 0); PG8_LDB(B1, 0, 1); PG8_SCHED; PG8_LDA(At, 0, 0); PG8_STAGE(PG8_SA(1, 1), a1 + hstepA, voffA);
;             PG8_WAIT_V(8); PG8_WAIT_L(0); PG8_BAR; PG8_MMA(0, 0, At, B0); PG8_MMA(0, 1, At, B1); PG8_BAR; PG8_SCHED;
;             PG8_LDA(At, 0, 1); PG8_STAGE(PG8_SB(0, 0), b2, voffB); PG8_STAGE(PG8_SB(0, 1), b2 + hstepB, voffB); PG8_STAGE(PG8_SA(0, 0), a2, voffA);
;             PG8_WAIT_V(8); PG8_WAIT_L(0); PG8_BAR; PG8_MMA(1, 0, At, B0); PG8_MMA(1, 1, At, B1); PG8_BAR; PG8_SCHED;
.LBB0_1132:
	s_ashr_i32 s35, s34, 31
	s_lshl_b64 s[36:37], s[34:35], 19
	s_add_u32 s36, s28, s36
	s_addc_u32 s37, s29, s37
	s_and_b64 s[38:39], s[6:7], exec
	s_cselect_b32 s35, s37, s45
	s_cselect_b32 s41, s36, s44
	s_ashr_i32 s21, s20, 31
	s_lshl_b64 s[38:39], s[20:21], 19
	s_add_u32 s38, s50, s38
	s_addc_u32 s39, s51, s39
	s_and_b64 s[48:49], s[6:7], exec
	s_cselect_b32 s21, s39, s47
	s_cselect_b32 s63, s38, s46
	s_add_u32 s44, s44, 0x40080
	s_addc_u32 s45, s45, 0
	s_add_u32 s64, s46, 0x100
	s_addc_u32 s65, s47, 0
	s_mov_b32 s66, -2
	s_waitcnt lgkmcnt(0)
	s_waitcnt vmcnt(0)
	ds_read_b128 v[146:149], v152
	ds_read_b128 v[156:159], v152 offset:1024
	ds_read_b128 v[160:163], v152 offset:2048
	ds_read_b128 v[164:167], v152 offset:3072
	ds_read_b128 v[168:171], v153
	ds_read_b128 v[172:175], v153 offset:1024
	ds_read_b128 v[176:179], v153 offset:2048
	ds_read_b128 v[180:183], v153 offset:3072
	s_add_u32 s46, s44, 0xfffc0080
	s_addc_u32 s47, s45, -1
	s_cmp_eq_u32 s66, 12
	s_cselect_b32 s49, s35, s47
	s_cselect_b32 s48, s41, s46
	s_cselect_b32 s47, s21, s65
	s_cselect_b32 s46, s63, s64
	v_lshl_add_u64 v[218:219], s[44:45], 0, v[138:139]
	s_add_i32 m0, s43, 0xc000
	ds_read_b128 v[186:189], v154
	ds_read_b128 v[190:193], v154 offset:1024
	ds_read_b128 v[194:197], v154 offset:2048
	ds_read_b128 v[198:201], v154 offset:3072
	ds_read_b128 v[202:205], v154 offset:4096
	ds_read_b128 v[206:209], v154 offset:5120
	ds_read_b128 v[210:213], v154 offset:6144
	ds_read_b128 v[214:217], v154 offset:7168
	global_load_lds_dwordx4 v[218:219], off
	v_lshl_add_u64 v[218:219], s[44:45], 0, v[140:141]
	s_add_i32 m0, s43, 0xe000
	s_nop 0
	global_load_lds_dwordx4 v[218:219], off
	s_waitcnt vmcnt(8)
	s_waitcnt lgkmcnt(0)
	s_barrier
	s_setprio 1
	s_waitcnt lgkmcnt(0)
	v_mfma_f32_16x16x32_bf16 v[126:129], v[146:149], v[186:189], 0
	v_mfma_f32_16x16x32_bf16 v[122:125], v[160:163], v[186:189], 0
	v_mfma_f32_16x16x32_bf16 v[110:113], v[146:149], v[194:197], 0
	v_mfma_f32_16x16x32_bf16 v[106:109], v[160:163], v[194:197], 0
	v_mfma_f32_16x16x32_bf16 v[94:97], v[146:149], v[202:205], 0
	v_mfma_f32_16x16x32_bf16 v[90:93], v[160:163], v[202:205], 0
	v_mfma_f32_16x16x32_bf16 v[78:81], v[146:149], v[210:213], 0
	v_mfma_f32_16x16x32_bf16 v[74:77], v[160:163], v[210:213], 0
	v_mfma_f32_16x16x32_bf16 v[126:129], v[156:159], v[190:193], v[126:129]
	v_mfma_f32_16x16x32_bf16 v[122:125], v[164:167], v[190:193], v[122:125]
	v_mfma_f32_16x16x32_bf16 v[110:113], v[156:159], v[198:201], v[110:113]
	v_mfma_f32_16x16x32_bf16 v[106:109], v[164:167], v[198:201], v[106:109]
	v_mfma_f32_16x16x32_bf16 v[94:97], v[156:159], v[206:209], v[94:97]
	v_mfma_f32_16x16x32_bf16 v[90:93], v[164:167], v[206:209], v[90:93]
	v_mfma_f32_16x16x32_bf16 v[78:81], v[156:159], v[214:217], v[78:81]
	v_mfma_f32_16x16x32_bf16 v[74:77], v[164:167], v[214:217], v[74:77]
	s_setprio 0
	s_setprio 1
	v_mfma_f32_16x16x32_bf16 v[118:121], v[168:171], v[186:189], 0
	v_mfma_f32_16x16x32_bf16 v[114:117], v[176:179], v[186:189], 0
	v_mfma_f32_16x16x32_bf16 v[102:105], v[168:171], v[194:197], 0
	v_mfma_f32_16x16x32_bf16 v[98:101], v[176:179], v[194:197], 0
	v_mfma_f32_16x16x32_bf16 v[86:89], v[168:171], v[202:205], 0
	v_mfma_f32_16x16x32_bf16 v[82:85], v[176:179], v[202:205], 0
	v_mfma_f32_16x16x32_bf16 v[70:73], v[168:171], v[210:213], 0
	v_mfma_f32_16x16x32_bf16 v[66:69], v[176:179], v[210:213], 0
	v_mfma_f32_16x16x32_bf16 v[118:121], v[172:175], v[190:193], v[118:121]
	v_mfma_f32_16x16x32_bf16 v[114:117], v[180:183], v[190:193], v[114:117]
	v_mfma_f32_16x16x32_bf16 v[102:105], v[172:175], v[198:201], v[102:105]
	v_mfma_f32_16x16x32_bf16 v[98:101], v[180:183], v[198:201], v[98:101]
	v_mfma_f32_16x16x32_bf16 v[86:89], v[172:175], v[206:209], v[86:89]
	v_mfma_f32_16x16x32_bf16 v[82:85], v[180:183], v[206:209], v[82:85]
	v_mfma_f32_16x16x32_bf16 v[70:73], v[172:175], v[214:217], v[70:73]
	v_mfma_f32_16x16x32_bf16 v[66:69], v[180:183], v[214:217], v[66:69]
	s_setprio 0
	s_barrier
	s_add_i32 s67, s61, s52
	v_lshl_add_u64 v[218:219], s[46:47], 0, v[132:133]
	s_mov_b32 m0, s67
	ds_read_b128 v[186:189], v154 offset:16384
	ds_read_b128 v[190:193], v154 offset:17408
	ds_read_b128 v[194:197], v154 offset:18432
	ds_read_b128 v[198:201], v154 offset:19456
	ds_read_b128 v[202:205], v154 offset:20480
	ds_read_b128 v[206:209], v154 offset:21504
	ds_read_b128 v[210:213], v154 offset:22528
	ds_read_b128 v[214:217], v154 offset:23552
	global_load_lds_dwordx4 v[218:219], off
	s_add_i32 m0, s67, 0x2000
	s_add_u32 s68, s46, 0x40000
	v_lshl_add_u64 v[220:221], s[46:47], 0, v[136:137]
	s_addc_u32 s69, s47, 0
	s_add_i32 s67, s62, s52
	global_load_lds_dwordx4 v[220:221], off
	v_lshl_add_u64 v[222:223], s[68:69], 0, v[132:133]
	s_mov_b32 m0, s67
	v_lshl_add_u64 v[224:225], s[48:49], 0, v[134:135]
	global_load_lds_dwordx4 v[222:223], off
	v_lshl_add_u64 v[222:223], s[68:69], 0, v[136:137]
	s_add_i32 m0, s67, 0x2000
	s_nop 0
	global_load_lds_dwordx4 v[222:223], off
	v_lshl_add_u64 v[222:223], s[48:49], 0, v[130:131]
	s_mov_b32 m0, s43
	s_nop 0
	global_load_lds_dwordx4 v[222:223], off
	s_mov_b32 m0, s53
	s_nop 0
	global_load_lds_dwordx4 v[224:225], off
	s_waitcnt vmcnt(8)
	s_waitcnt lgkmcnt(0)
	s_barrier
; #define PG8_STAGE(bufoff, gbase, voff) do { _Pragma("unroll") for (int _i = 0; _i < 2; ++_i) \
;         __builtin_amdgcn_global_load_lds((const unsigned*)((const char*)(gbase) + (voff)[_i]), (LAS unsigned*)(lds + (bufoff) + ldsw + _i * 8192), 16, 0, 0); } while (0)
; #define PG8_LDA(dst, b, h) do { _Pragma("unroll") for (int m = 0; m < 4; ++m) _Pragma("unroll") for (int k = 0; k < 2; ++k) dst[m][k] = *(const LAS bf16x8*)(lds + PG8_SA(b, h) + aoff + m * 2048 + k * 1024); } while (0)
; #define PG8_LDB(dst, b, h) do { _Pragma("unroll") for (int n = 0; n < 2; ++n) _Pragma("unroll") for (int k = 0; k < 2; ++k) dst[n][k] = *(const LAS bf16x8*)(lds + PG8_SB(b, h) + boff + n * 2048 + k * 1024); } while (0)
; #define PG8_MMA(ai, bj, At, Bt) do { __builtin_amdgcn_s_setprio(1); _Pragma("unroll") for (int m = 0; m < 4; ++m) _Pragma("unroll") for (int n = 0; n < 2; ++n) _Pragma("unroll") for (int k = 0; k < 2; ++k) \
;         acc[ai][bj][m][n] = __builtin_amdgcn_mfma_f32_16x16x32_bf16(Bt[n][k], At[m][k], acc[ai][bj][m][n], 0, 0, 0); __builtin_amdgcn_s_setprio(0); } while (0)
; #define PG8_WAIT_V(n) asm volatile("s_waitcnt vmcnt(" #n ")" ::: "memory")
; #define PG8_WAIT_L(n) asm volatile("s_waitcnt lgkmcnt(" #n ")" ::: "memory")
; #define PG8_BAR __builtin_amdgcn_s_barrier()
; #define PG8_SCHED __builtin_amdgcn_sched_barrier(0)
; template <class Epi, class Sched>
; DI void gemm_phase(LAS unsigned char* lds, const Gemm g, const Sched& S, const Epi& E) {
;     ...
;             PG8_WAIT_V(8); PG8_WAIT_L(0); PG8_BAR; PG8_MMA(1, 0, At, B0); PG8_MMA(1, 1, At, B1); PG8_BAR; PG8_SCHED;
;             PG8_LDB(B0, 1, 0); PG8_LDB(B1, 1, 1); PG8_SCHED; PG8_LDA(At, 1, 0); PG8_STAGE(PG8_SA(0, 1), a2 + hstepA, voffA);
;             PG8_WAIT_V(8); PG8_WAIT_L(0); PG8_BAR; PG8_MMA(0, 0, At, B0); PG8_MMA(0, 1, At, B1); PG8_BAR; PG8_SCHED;
	s_setprio 1
	s_waitcnt lgkmcnt(0)
	v_mfma_f32_16x16x32_bf16 v[62:65], v[146:149], v[186:189], 0
	v_mfma_f32_16x16x32_bf16 v[58:61], v[160:163], v[186:189], 0
	v_mfma_f32_16x16x32_bf16 v[46:49], v[146:149], v[194:197], 0
	v_mfma_f32_16x16x32_bf16 v[42:45], v[160:163], v[194:197], 0
	v_mfma_f32_16x16x32_bf16 v[30:33], v[146:149], v[202:205], 0
	v_mfma_f32_16x16x32_bf16 v[26:29], v[160:163], v[202:205], 0
	v_mfma_f32_16x16x32_bf16 v[14:17], v[146:149], v[210:213], 0
	v_mfma_f32_16x16x32_bf16 v[10:13], v[160:163], v[210:213], 0
	v_mfma_f32_16x16x32_bf16 v[62:65], v[156:159], v[190:193], v[62:65]
	v_mfma_f32_16x16x32_bf16 v[58:61], v[164:167], v[190:193], v[58:61]
	v_mfma_f32_16x16x32_bf16 v[46:49], v[156:159], v[198:201], v[46:49]
	v_mfma_f32_16x16x32_bf16 v[42:45], v[164:167], v[198:201], v[42:45]
	v_mfma_f32_16x16x32_bf16 v[30:33], v[156:159], v[206:209], v[30:33]
	v_mfma_f32_16x16x32_bf16 v[26:29], v[164:167], v[206:209], v[26:29]
	v_mfma_f32_16x16x32_bf16 v[14:17], v[156:159], v[214:217], v[14:17]
	v_mfma_f32_16x16x32_bf16 v[10:13], v[164:167], v[214:217], v[10:13]
	s_setprio 0
	s_setprio 1
	v_mfma_f32_16x16x32_bf16 v[54:57], v[168:171], v[186:189], 0
	v_mfma_f32_16x16x32_bf16 v[50:53], v[176:179], v[186:189], 0
	v_mfma_f32_16x16x32_bf16 v[38:41], v[168:171], v[194:197], 0
	v_mfma_f32_16x16x32_bf16 v[34:37], v[176:179], v[194:197], 0
	v_mfma_f32_16x16x32_bf16 v[22:25], v[168:171], v[202:205], 0
	v_mfma_f32_16x16x32_bf16 v[18:21], v[176:179], v[202:205], 0
	v_mfma_f32_16x16x32_bf16 v[6:9], v[168:171], v[210:213], 0
	v_mfma_f32_16x16x32_bf16 v[2:5], v[176:179], v[210:213], 0
	v_mfma_f32_16x16x32_bf16 v[54:57], v[172:175], v[190:193], v[54:57]
	v_mfma_f32_16x16x32_bf16 v[50:53], v[180:183], v[190:193], v[50:53]
	v_mfma_f32_16x16x32_bf16 v[38:41], v[172:175], v[198:201], v[38:41]
	v_mfma_f32_16x16x32_bf16 v[34:37], v[180:183], v[198:201], v[34:37]
	v_mfma_f32_16x16x32_bf16 v[22:25], v[172:175], v[206:209], v[22:25]
	v_mfma_f32_16x16x32_bf16 v[18:21], v[180:183], v[206:209], v[18:21]
	v_mfma_f32_16x16x32_bf16 v[6:9], v[172:175], v[214:217], v[6:9]
	v_mfma_f32_16x16x32_bf16 v[2:5], v[180:183], v[214:217], v[2:5]
	s_setprio 0
	s_barrier
	s_add_i32 s67, 0, 0x18000
	s_add_i32 s68, 0, 0x1c000
	v_add_u32_e32 v164, s67, v150
	v_add_u32_e32 v180, s68, v150
	ds_read_b128 v[146:149], v164
	ds_read_b128 v[156:159], v164 offset:1024
	ds_read_b128 v[160:163], v164 offset:2048
	ds_read_b128 v[164:167], v164 offset:3072
	ds_read_b128 v[168:171], v180
	ds_read_b128 v[172:175], v180 offset:1024
	ds_read_b128 v[176:179], v180 offset:2048
	ds_read_b128 v[180:183], v180 offset:3072
	s_add_u32 s48, s48, 0x40000
	s_addc_u32 s49, s49, 0
	s_mov_b32 m0, s54
	v_lshl_add_u64 v[226:227], s[48:49], 0, v[130:131]
	ds_read_b128 v[186:189], v154 offset:32768
	ds_read_b128 v[190:193], v154 offset:33792
	ds_read_b128 v[194:197], v154 offset:34816
	ds_read_b128 v[198:201], v154 offset:35840
	ds_read_b128 v[202:205], v154 offset:36864
	ds_read_b128 v[206:209], v154 offset:37888
	ds_read_b128 v[210:213], v154 offset:38912
	ds_read_b128 v[214:217], v154 offset:39936
	global_load_lds_dwordx4 v[226:227], off
	v_lshl_add_u64 v[226:227], s[48:49], 0, v[134:135]
	s_mov_b32 m0, s55
	s_nop 0
	global_load_lds_dwordx4 v[226:227], off
	s_waitcnt vmcnt(8)
	s_waitcnt lgkmcnt(0)
	s_barrier
	s_setprio 1
	s_waitcnt lgkmcnt(0)
	v_mfma_f32_16x16x32_bf16 v[126:129], v[146:149], v[186:189], v[126:129]
	v_mfma_f32_16x16x32_bf16 v[122:125], v[160:163], v[186:189], v[122:125]
	v_mfma_f32_16x16x32_bf16 v[110:113], v[146:149], v[194:197], v[110:113]
	v_mfma_f32_16x16x32_bf16 v[106:109], v[160:163], v[194:197], v[106:109]
	v_mfma_f32_16x16x32_bf16 v[94:97], v[146:149], v[202:205], v[94:97]
	v_mfma_f32_16x16x32_bf16 v[90:93], v[160:163], v[202:205], v[90:93]
	v_mfma_f32_16x16x32_bf16 v[78:81], v[146:149], v[210:213], v[78:81]
	v_mfma_f32_16x16x32_bf16 v[74:77], v[160:163], v[210:213], v[74:77]
	v_mfma_f32_16x16x32_bf16 v[126:129], v[156:159], v[190:193], v[126:129]
	v_mfma_f32_16x16x32_bf16 v[122:125], v[164:167], v[190:193], v[122:125]
	v_mfma_f32_16x16x32_bf16 v[110:113], v[156:159], v[198:201], v[110:113]
	v_mfma_f32_16x16x32_bf16 v[106:109], v[164:167], v[198:201], v[106:109]
	v_mfma_f32_16x16x32_bf16 v[94:97], v[156:159], v[206:209], v[94:97]
	v_mfma_f32_16x16x32_bf16 v[90:93], v[164:167], v[206:209], v[90:93]
	v_mfma_f32_16x16x32_bf16 v[78:81], v[156:159], v[214:217], v[78:81]
	v_mfma_f32_16x16x32_bf16 v[74:77], v[164:167], v[214:217], v[74:77]
	s_setprio 0
	s_setprio 1
	v_mfma_f32_16x16x32_bf16 v[118:121], v[168:171], v[186:189], v[118:121]
	v_mfma_f32_16x16x32_bf16 v[114:117], v[176:179], v[186:189], v[114:117]
	v_mfma_f32_16x16x32_bf16 v[102:105], v[168:171], v[194:197], v[102:105]
	v_mfma_f32_16x16x32_bf16 v[98:101], v[176:179], v[194:197], v[98:101]
	v_mfma_f32_16x16x32_bf16 v[86:89], v[168:171], v[202:205], v[86:89]
	v_mfma_f32_16x16x32_bf16 v[82:85], v[176:179], v[202:205], v[82:85]
	v_mfma_f32_16x16x32_bf16 v[70:73], v[168:171], v[210:213], v[70:73]
	v_mfma_f32_16x16x32_bf16 v[66:69], v[176:179], v[210:213], v[66:69]
	v_mfma_f32_16x16x32_bf16 v[118:121], v[172:175], v[190:193], v[118:121]
	v_mfma_f32_16x16x32_bf16 v[114:117], v[180:183], v[190:193], v[114:117]
	v_mfma_f32_16x16x32_bf16 v[102:105], v[172:175], v[198:201], v[102:105]
	v_mfma_f32_16x16x32_bf16 v[98:101], v[180:183], v[198:201], v[98:101]
	v_mfma_f32_16x16x32_bf16 v[86:89], v[172:175], v[206:209], v[86:89]
	v_mfma_f32_16x16x32_bf16 v[82:85], v[180:183], v[206:209], v[82:85]
	v_mfma_f32_16x16x32_bf16 v[70:73], v[172:175], v[214:217], v[70:73]
	v_mfma_f32_16x16x32_bf16 v[66:69], v[180:183], v[214:217], v[66:69]
	s_setprio 0
	s_barrier
; #define PG8_STAGE(bufoff, gbase, voff) do { _Pragma("unroll") for (int _i = 0; _i < 2; ++_i) \
;         __builtin_amdgcn_global_load_lds((const unsigned*)((const char*)(gbase) + (voff)[_i]), (LAS unsigned*)(lds + (bufoff) + ldsw + _i * 8192), 16, 0, 0); } while (0)
; #define PG8_LDA(dst, b, h) do { _Pragma("unroll") for (int m = 0; m < 4; ++m) _Pragma("unroll") for (int k = 0; k < 2; ++k) dst[m][k] = *(const LAS bf16x8*)(lds + PG8_SA(b, h) + aoff + m * 2048 + k * 1024); } while (0)
; #define PG8_MMA(ai, bj, At, Bt) do { __builtin_amdgcn_s_setprio(1); _Pragma("unroll") for (int m = 0; m < 4; ++m) _Pragma("unroll") for (int n = 0; n < 2; ++n) _Pragma("unroll") for (int k = 0; k < 2; ++k) \
;         acc[ai][bj][m][n] = __builtin_amdgcn_mfma_f32_16x16x32_bf16(Bt[n][k], At[m][k], acc[ai][bj][m][n], 0, 0, 0); __builtin_amdgcn_s_setprio(0); } while (0)
; #define PG8_WAIT_V(n) asm volatile("s_waitcnt vmcnt(" #n ")" ::: "memory")
; #define PG8_WAIT_L(n) asm volatile("s_waitcnt lgkmcnt(" #n ")" ::: "memory")
; #define PG8_BAR __builtin_amdgcn_s_barrier()
; #define PG8_SCHED __builtin_amdgcn_sched_barrier(0)
; template <class Epi, class Sched>
; DI void gemm_phase(LAS unsigned char* lds, const Gemm g, const Sched& S, const Epi& E) {
;     ...
;             PG8_WAIT_V(8); PG8_WAIT_L(0); PG8_BAR; PG8_MMA(0, 0, At, B0); PG8_MMA(0, 1, At, B1); PG8_BAR; PG8_SCHED;
;             PG8_LDA(At, 1, 1); PG8_STAGE(PG8_SB(1, 0), b3, voffB); PG8_STAGE(PG8_SB(1, 1), b3 + hstepB, voffB); PG8_STAGE(PG8_SA(1, 0), a3, voffA);
;             PG8_WAIT_V(8); PG8_WAIT_L(0); PG8_BAR; PG8_MMA(1, 0, At, B0); PG8_MMA(1, 1, At, B1); PG8_BAR; PG8_SCHED;
;         }
	s_add_i32 s48, s67, s52
	v_lshl_add_u64 v[218:219], v[218:219], 0, s[16:17]
	s_mov_b32 m0, s48
	ds_read_b128 v[186:189], v154 offset:49152
	ds_read_b128 v[190:193], v154 offset:50176
	ds_read_b128 v[194:197], v154 offset:51200
	ds_read_b128 v[198:201], v154 offset:52224
	ds_read_b128 v[202:205], v154 offset:53248
	ds_read_b128 v[206:209], v154 offset:54272
	ds_read_b128 v[210:213], v154 offset:55296
	ds_read_b128 v[214:217], v154 offset:56320
	global_load_lds_dwordx4 v[218:219], off
	s_add_i32 m0, s48, 0x2000
	s_add_u32 s46, s46, 0x40080
	v_lshl_add_u64 v[218:219], v[220:221], 0, s[16:17]
	s_addc_u32 s47, s47, 0
	s_add_i32 s48, s68, s52
	global_load_lds_dwordx4 v[218:219], off
	v_lshl_add_u64 v[218:219], s[46:47], 0, v[132:133]
	s_mov_b32 m0, s48
	s_nop 0
	global_load_lds_dwordx4 v[218:219], off
	v_lshl_add_u64 v[218:219], s[46:47], 0, v[136:137]
	s_add_i32 m0, s48, 0x2000
	s_nop 0
	global_load_lds_dwordx4 v[218:219], off
	v_lshl_add_u64 v[218:219], v[222:223], 0, s[16:17]
	s_mov_b32 m0, s57
	s_nop 0
	global_load_lds_dwordx4 v[218:219], off
	v_lshl_add_u64 v[218:219], v[224:225], 0, s[16:17]
	s_mov_b32 m0, s58
	s_nop 0
	global_load_lds_dwordx4 v[218:219], off
	s_waitcnt vmcnt(8)
	s_waitcnt lgkmcnt(0)
	s_barrier
	s_setprio 1
	s_waitcnt lgkmcnt(0)
	v_mfma_f32_16x16x32_bf16 v[62:65], v[146:149], v[186:189], v[62:65]
	v_mfma_f32_16x16x32_bf16 v[58:61], v[160:163], v[186:189], v[58:61]
	v_mfma_f32_16x16x32_bf16 v[46:49], v[146:149], v[194:197], v[46:49]
	v_mfma_f32_16x16x32_bf16 v[42:45], v[160:163], v[194:197], v[42:45]
	v_mfma_f32_16x16x32_bf16 v[30:33], v[146:149], v[202:205], v[30:33]
	v_mfma_f32_16x16x32_bf16 v[26:29], v[160:163], v[202:205], v[26:29]
	v_mfma_f32_16x16x32_bf16 v[14:17], v[146:149], v[210:213], v[14:17]
	v_mfma_f32_16x16x32_bf16 v[10:13], v[160:163], v[210:213], v[10:13]
	v_mfma_f32_16x16x32_bf16 v[62:65], v[156:159], v[190:193], v[62:65]
	v_mfma_f32_16x16x32_bf16 v[58:61], v[164:167], v[190:193], v[58:61]
	v_mfma_f32_16x16x32_bf16 v[46:49], v[156:159], v[198:201], v[46:49]
	v_mfma_f32_16x16x32_bf16 v[42:45], v[164:167], v[198:201], v[42:45]
	v_mfma_f32_16x16x32_bf16 v[30:33], v[156:159], v[206:209], v[30:33]
	v_mfma_f32_16x16x32_bf16 v[26:29], v[164:167], v[206:209], v[26:29]
	v_mfma_f32_16x16x32_bf16 v[14:17], v[156:159], v[214:217], v[14:17]
	v_mfma_f32_16x16x32_bf16 v[10:13], v[164:167], v[214:217], v[10:13]
	s_setprio 0
	s_setprio 1
	v_mfma_f32_16x16x32_bf16 v[54:57], v[168:171], v[186:189], v[54:57]
	v_mfma_f32_16x16x32_bf16 v[50:53], v[176:179], v[186:189], v[50:53]
	v_mfma_f32_16x16x32_bf16 v[38:41], v[168:171], v[194:197], v[38:41]
	v_mfma_f32_16x16x32_bf16 v[34:37], v[176:179], v[194:197], v[34:37]
	v_mfma_f32_16x16x32_bf16 v[22:25], v[168:171], v[202:205], v[22:25]
	v_mfma_f32_16x16x32_bf16 v[18:21], v[176:179], v[202:205], v[18:21]
	v_mfma_f32_16x16x32_bf16 v[6:9], v[168:171], v[210:213], v[6:9]
	v_mfma_f32_16x16x32_bf16 v[2:5], v[176:179], v[210:213], v[2:5]
	v_mfma_f32_16x16x32_bf16 v[54:57], v[172:175], v[190:193], v[54:57]
	v_mfma_f32_16x16x32_bf16 v[50:53], v[180:183], v[190:193], v[50:53]
	v_mfma_f32_16x16x32_bf16 v[38:41], v[172:175], v[198:201], v[38:41]
	v_mfma_f32_16x16x32_bf16 v[34:37], v[180:183], v[198:201], v[34:37]
	v_mfma_f32_16x16x32_bf16 v[22:25], v[172:175], v[206:209], v[22:25]
	v_mfma_f32_16x16x32_bf16 v[18:21], v[180:183], v[206:209], v[18:21]
	v_mfma_f32_16x16x32_bf16 v[6:9], v[172:175], v[214:217], v[6:9]
	v_mfma_f32_16x16x32_bf16 v[2:5], v[180:183], v[214:217], v[2:5]
	s_setprio 0
	s_barrier
	s_add_i32 s66, s66, 2
	s_add_u32 s44, s44, 0x100
	s_addc_u32 s45, s45, 0
	s_add_u32 s64, s64, 0x100
	s_addc_u32 s65, s65, 0
	s_cmp_gt_u32 s66, 13

;     DI bool next(int i, Unit& u) const { if (i > 0 || c >= 64) return false; u.pm = c & 31; u.pn = 0; u.src = c >> 5; return true; }
; #define PG8_STAGE(bufoff, gbase, voff) do { _Pragma("unroll") for (int _i = 0; _i < 2; ++_i) \
;         __builtin_amdgcn_global_load_lds((const unsigned*)((const char*)(gbase) + (voff)[_i]), (LAS unsigned*)(lds + (bufoff) + ldsw + _i * 8192), 16, 0, 0); } while (0)
; #define PG8_LDA(dst, b, h) do { _Pragma("unroll") for (int m = 0; m < 4; ++m) _Pragma("unroll") for (int k = 0; k < 2; ++k) dst[m][k] = *(const LAS bf16x8*)(lds + PG8_SA(b, h) + aoff + m * 2048 + k * 1024); } while (0)
; #define PG8_LDB(dst, b, h) do { _Pragma("unroll") for (int n = 0; n < 2; ++n) _Pragma("unroll") for (int k = 0; k < 2; ++k) dst[n][k] = *(const LAS bf16x8*)(lds + PG8_SB(b, h) + boff + n * 2048 + k * 1024); } while (0)
; #define PG8_WAIT_V(n) asm volatile("s_waitcnt vmcnt(" #n ")" ::: "memory")
; #define PG8_WAIT_L(n) asm volatile("s_waitcnt lgkmcnt(" #n ")" ::: "memory")
; #define PG8_BAR __builtin_amdgcn_s_barrier()
; #define PG8_SCHED __builtin_amdgcn_sched_barrier(0)
; template <class Epi, class Sched>
; DI void gemm_phase(LAS unsigned char* lds, const Gemm g, const Sched& S, const Epi& E) {
;     ...
;         const bool has_next = S.next(ui + 1, nxt);
;         E.pre(pre, cur, wr, fr);
;         const char* nA = has_next ? (const char*)(nxt.src ? g.A1 : g.A0) + (size_t)nxt.pm * tstepA : cA; const char* nB = has_next ? (const char*)(nxt.src ? g.B1 : g.B0) + (size_t)nxt.pn * tstepB : cB;
;         for (int t = 0; t < nt; t += 2) {
;             const bool last = (t == nt - 2);
;             const char* a1 = cA + (size_t)(t + 1) * kstep;
;             const char* a2 = last ? nA : cA + (size_t)(t + 2) * kstep; const char* b2 = last ? nB : cB + (size_t)(t + 2) * kstep;
;             const char* a3 = a2 + kstep; const char* b3 = b2 + kstep;
;             PG8_LDB(B0, 0, 0); PG8_LDB(B1, 0, 1); PG8_SCHED; PG8_LDA(At, 0, 0); PG8_STAGE(PG8_SA(1, 1), a1 + hstepA, voffA);
;             PG8_WAIT_V(8); PG8_WAIT_L(0); PG8_BAR; PG8_MMA(0, 0, At, B0); PG8_MMA(0, 1, At, B1); PG8_BAR; PG8_SCHED;
;             PG8_LDA(At, 0, 1); PG8_STAGE(PG8_SB(0, 0), b2, voffB); PG8_STAGE(PG8_SB(0, 1), b2 + hstepB, voffB); PG8_STAGE(PG8_SA(0, 0), a2, voffA);
;             PG8_WAIT_V(8); PG8_WAIT_L(0); PG8_BAR; PG8_MMA(1, 0, At, B0); PG8_MMA(1, 1, At, B1); PG8_BAR; PG8_SCHED;
.LBB0_1233:
	v_lshl_add_u32 v154, s44, 8, v1
	v_ashrrev_i32_e32 v155, 31, v154
	v_add_u32_e32 v152, 0x80, v154
	v_add_u32_e32 v150, 0x90, v154
	v_add_u32_e32 v148, 0xa0, v154
	v_add_u32_e32 v146, 0xb0, v154
	v_lshl_add_u64 v[2:3], v[154:155], 2, s[8:9]
	v_ashrrev_i32_e32 v153, 31, v152
	v_ashrrev_i32_e32 v151, 31, v150
	v_ashrrev_i32_e32 v149, 31, v148
	v_ashrrev_i32_e32 v147, 31, v146
	v_lshl_add_u64 v[4:5], v[152:153], 2, s[8:9]
	v_lshl_add_u64 v[6:7], v[150:151], 2, s[8:9]
	v_lshl_add_u64 v[8:9], v[148:149], 2, s[8:9]
	v_lshl_add_u64 v[10:11], v[146:147], 2, s[8:9]
	global_load_dword v164, v[2:3], off
	global_load_dword v163, v[2:3], off offset:64
	global_load_dword v162, v[2:3], off offset:128
	global_load_dword v155, v[2:3], off offset:192
	global_load_dword v153, v[4:5], off
	global_load_dword v151, v[6:7], off
	global_load_dword v149, v[8:9], off
	global_load_dword v147, v[10:11], off
	s_ashr_i32 s35, s34, 31
	s_lshl_b64 s[36:37], s[34:35], 19
	s_add_u32 s36, s30, s36
	s_addc_u32 s37, s31, s37
	s_and_b64 s[38:39], s[4:5], exec
	s_cselect_b32 s35, s37, s41
	s_cselect_b32 s61, s36, s40
	s_ashr_i32 s21, s20, 31
	s_lshl_b64 s[38:39], s[20:21], 19
	s_add_u32 s38, s28, s38
	s_addc_u32 s39, s29, s39
	s_and_b64 s[44:45], s[4:5], exec
	s_cselect_b32 s21, s39, s43
	s_cselect_b32 s62, s38, s42
	s_add_u32 s40, s40, 0x40080
	s_addc_u32 s41, s41, 0
	s_add_u32 s63, s42, 0x100
	s_addc_u32 s64, s43, 0
	s_mov_b32 s65, -2
	s_waitcnt vmcnt(0)
	ds_read_b128 v[166:169], v160
	ds_read_b128 v[170:173], v160 offset:1024
	ds_read_b128 v[174:177], v160 offset:2048
	ds_read_b128 v[178:181], v160 offset:3072
	ds_read_b128 v[186:189], v161
	ds_read_b128 v[190:193], v161 offset:1024
	ds_read_b128 v[194:197], v161 offset:2048
	ds_read_b128 v[198:201], v161 offset:3072
	s_add_u32 s42, s40, 0xfffc0080
	s_addc_u32 s43, s41, -1
	s_cmp_eq_u32 s65, 12
	s_cselect_b32 s45, s35, s43
	s_cselect_b32 s44, s61, s42
	s_cselect_b32 s43, s21, s64
	s_cselect_b32 s42, s62, s63
	v_lshl_add_u64 v[182:183], s[40:41], 0, v[138:139]
	s_add_i32 m0, s49, 0xc000
	ds_read_b128 v[202:205], v158
	ds_read_b128 v[206:209], v158 offset:1024
	ds_read_b128 v[210:213], v158 offset:2048
	ds_read_b128 v[214:217], v158 offset:3072
	ds_read_b128 v[218:221], v158 offset:4096
	ds_read_b128 v[222:225], v158 offset:5120
	ds_read_b128 v[226:229], v158 offset:6144
	ds_read_b128 v[230:233], v158 offset:7168
	global_load_lds_dwordx4 v[182:183], off
	v_lshl_add_u64 v[182:183], s[40:41], 0, v[140:141]
	s_add_i32 m0, s49, 0xe000
	s_nop 0
	global_load_lds_dwordx4 v[182:183], off
	s_waitcnt vmcnt(8)
	s_waitcnt lgkmcnt(0)
	s_barrier
	s_setprio 1
	s_waitcnt lgkmcnt(0)
	v_mfma_f32_16x16x32_bf16 v[126:129], v[166:169], v[202:205], 0
	v_mfma_f32_16x16x32_bf16 v[118:121], v[174:177], v[202:205], 0
	v_mfma_f32_16x16x32_bf16 v[110:113], v[166:169], v[210:213], 0
	v_mfma_f32_16x16x32_bf16 v[102:105], v[174:177], v[210:213], 0
	v_mfma_f32_16x16x32_bf16 v[94:97], v[166:169], v[218:221], 0
	v_mfma_f32_16x16x32_bf16 v[86:89], v[174:177], v[218:221], 0
	v_mfma_f32_16x16x32_bf16 v[78:81], v[166:169], v[226:229], 0
	v_mfma_f32_16x16x32_bf16 v[70:73], v[174:177], v[226:229], 0
	v_mfma_f32_16x16x32_bf16 v[126:129], v[170:173], v[206:209], v[126:129]
	v_mfma_f32_16x16x32_bf16 v[118:121], v[178:181], v[206:209], v[118:121]
	v_mfma_f32_16x16x32_bf16 v[110:113], v[170:173], v[214:217], v[110:113]
	v_mfma_f32_16x16x32_bf16 v[102:105], v[178:181], v[214:217], v[102:105]
	v_mfma_f32_16x16x32_bf16 v[94:97], v[170:173], v[222:225], v[94:97]
	v_mfma_f32_16x16x32_bf16 v[86:89], v[178:181], v[222:225], v[86:89]
	v_mfma_f32_16x16x32_bf16 v[78:81], v[170:173], v[230:233], v[78:81]
	v_mfma_f32_16x16x32_bf16 v[70:73], v[178:181], v[230:233], v[70:73]
	s_setprio 0
	s_setprio 1
	v_mfma_f32_16x16x32_bf16 v[122:125], v[186:189], v[202:205], 0
	v_mfma_f32_16x16x32_bf16 v[114:117], v[194:197], v[202:205], 0
	v_mfma_f32_16x16x32_bf16 v[106:109], v[186:189], v[210:213], 0
	v_mfma_f32_16x16x32_bf16 v[98:101], v[194:197], v[210:213], 0
	v_mfma_f32_16x16x32_bf16 v[90:93], v[186:189], v[218:221], 0
	v_mfma_f32_16x16x32_bf16 v[82:85], v[194:197], v[218:221], 0
	v_mfma_f32_16x16x32_bf16 v[74:77], v[186:189], v[226:229], 0
	v_mfma_f32_16x16x32_bf16 v[66:69], v[194:197], v[226:229], 0
	v_mfma_f32_16x16x32_bf16 v[122:125], v[190:193], v[206:209], v[122:125]
	v_mfma_f32_16x16x32_bf16 v[114:117], v[198:201], v[206:209], v[114:117]
	v_mfma_f32_16x16x32_bf16 v[106:109], v[190:193], v[214:217], v[106:109]
	v_mfma_f32_16x16x32_bf16 v[98:101], v[198:201], v[214:217], v[98:101]
	v_mfma_f32_16x16x32_bf16 v[90:93], v[190:193], v[222:225], v[90:93]
	v_mfma_f32_16x16x32_bf16 v[82:85], v[198:201], v[222:225], v[82:85]
	v_mfma_f32_16x16x32_bf16 v[74:77], v[190:193], v[230:233], v[74:77]
	v_mfma_f32_16x16x32_bf16 v[66:69], v[198:201], v[230:233], v[66:69]
	s_setprio 0
	s_barrier
	s_add_i32 s66, s57, s46
	v_lshl_add_u64 v[182:183], s[42:43], 0, v[134:135]
	s_mov_b32 m0, s66
	ds_read_b128 v[202:205], v158 offset:16384
	ds_read_b128 v[206:209], v158 offset:17408
	ds_read_b128 v[210:213], v158 offset:18432
	ds_read_b128 v[214:217], v158 offset:19456
	ds_read_b128 v[218:221], v158 offset:20480
	ds_read_b128 v[222:225], v158 offset:21504
	ds_read_b128 v[226:229], v158 offset:22528
	ds_read_b128 v[230:233], v158 offset:23552
	global_load_lds_dwordx4 v[182:183], off
	s_add_i32 m0, s66, 0x2000
	s_add_u32 s66, s42, 0x40000
	v_lshl_add_u64 v[234:235], s[42:43], 0, v[130:131]
	s_addc_u32 s67, s43, 0
	s_add_i32 s68, s58, s46
	global_load_lds_dwordx4 v[234:235], off
	v_lshl_add_u64 v[236:237], s[66:67], 0, v[134:135]
	s_mov_b32 m0, s68
	v_lshl_add_u64 v[238:239], s[44:45], 0, v[132:133]
	global_load_lds_dwordx4 v[236:237], off
	v_lshl_add_u64 v[236:237], s[66:67], 0, v[130:131]
	s_add_i32 m0, s68, 0x2000
	s_nop 0
	global_load_lds_dwordx4 v[236:237], off
	v_lshl_add_u64 v[236:237], s[44:45], 0, v[136:137]
	s_mov_b32 m0, s49
	s_nop 0
	global_load_lds_dwordx4 v[236:237], off
	s_mov_b32 m0, s50
	s_nop 0
	global_load_lds_dwordx4 v[238:239], off
	s_waitcnt vmcnt(8)
	s_waitcnt lgkmcnt(0)
	s_barrier
; #define PG8_STAGE(bufoff, gbase, voff) do { _Pragma("unroll") for (int _i = 0; _i < 2; ++_i) \
;         __builtin_amdgcn_global_load_lds((const unsigned*)((const char*)(gbase) + (voff)[_i]), (LAS unsigned*)(lds + (bufoff) + ldsw + _i * 8192), 16, 0, 0); } while (0)
; #define PG8_LDA(dst, b, h) do { _Pragma("unroll") for (int m = 0; m < 4; ++m) _Pragma("unroll") for (int k = 0; k < 2; ++k) dst[m][k] = *(const LAS bf16x8*)(lds + PG8_SA(b, h) + aoff + m * 2048 + k * 1024); } while (0)
; #define PG8_LDB(dst, b, h) do { _Pragma("unroll") for (int n = 0; n < 2; ++n) _Pragma("unroll") for (int k = 0; k < 2; ++k) dst[n][k] = *(const LAS bf16x8*)(lds + PG8_SB(b, h) + boff + n * 2048 + k * 1024); } while (0)
; #define PG8_MMA(ai, bj, At, Bt) do { __builtin_amdgcn_s_setprio(1); _Pragma("unroll") for (int m = 0; m < 4; ++m) _Pragma("unroll") for (int n = 0; n < 2; ++n) _Pragma("unroll") for (int k = 0; k < 2; ++k) \
;         acc[ai][bj][m][n] = __builtin_amdgcn_mfma_f32_16x16x32_bf16(Bt[n][k], At[m][k], acc[ai][bj][m][n], 0, 0, 0); __builtin_amdgcn_s_setprio(0); } while (0)
; #define PG8_WAIT_V(n) asm volatile("s_waitcnt vmcnt(" #n ")" ::: "memory")
; #define PG8_WAIT_L(n) asm volatile("s_waitcnt lgkmcnt(" #n ")" ::: "memory")
; #define PG8_BAR __builtin_amdgcn_s_barrier()
; #define PG8_SCHED __builtin_amdgcn_sched_barrier(0)
; template <class Epi, class Sched>
; DI void gemm_phase(LAS unsigned char* lds, const Gemm g, const Sched& S, const Epi& E) {
;     ...
;             PG8_WAIT_V(8); PG8_WAIT_L(0); PG8_BAR; PG8_MMA(1, 0, At, B0); PG8_MMA(1, 1, At, B1); PG8_BAR; PG8_SCHED;
;             PG8_LDB(B0, 1, 0); PG8_LDB(B1, 1, 1); PG8_SCHED; PG8_LDA(At, 1, 0); PG8_STAGE(PG8_SA(0, 1), a2 + hstepA, voffA);
;             PG8_WAIT_V(8); PG8_WAIT_L(0); PG8_BAR; PG8_MMA(0, 0, At, B0); PG8_MMA(0, 1, At, B1); PG8_BAR; PG8_SCHED;
	s_setprio 1
	s_waitcnt lgkmcnt(0)
	v_mfma_f32_16x16x32_bf16 v[62:65], v[166:169], v[202:205], 0
	v_mfma_f32_16x16x32_bf16 v[54:57], v[174:177], v[202:205], 0
	v_mfma_f32_16x16x32_bf16 v[46:49], v[166:169], v[210:213], 0
	v_mfma_f32_16x16x32_bf16 v[38:41], v[174:177], v[210:213], 0
	v_mfma_f32_16x16x32_bf16 v[30:33], v[166:169], v[218:221], 0
	v_mfma_f32_16x16x32_bf16 v[22:25], v[174:177], v[218:221], 0
	v_mfma_f32_16x16x32_bf16 v[14:17], v[166:169], v[226:229], 0
	v_mfma_f32_16x16x32_bf16 v[6:9], v[174:177], v[226:229], 0
	v_mfma_f32_16x16x32_bf16 v[62:65], v[170:173], v[206:209], v[62:65]
	v_mfma_f32_16x16x32_bf16 v[54:57], v[178:181], v[206:209], v[54:57]
	v_mfma_f32_16x16x32_bf16 v[46:49], v[170:173], v[214:217], v[46:49]
	v_mfma_f32_16x16x32_bf16 v[38:41], v[178:181], v[214:217], v[38:41]
	v_mfma_f32_16x16x32_bf16 v[30:33], v[170:173], v[222:225], v[30:33]
	v_mfma_f32_16x16x32_bf16 v[22:25], v[178:181], v[222:225], v[22:25]
	v_mfma_f32_16x16x32_bf16 v[14:17], v[170:173], v[230:233], v[14:17]
	v_mfma_f32_16x16x32_bf16 v[6:9], v[178:181], v[230:233], v[6:9]
	s_setprio 0
	s_setprio 1
	v_mfma_f32_16x16x32_bf16 v[58:61], v[186:189], v[202:205], 0
	v_mfma_f32_16x16x32_bf16 v[50:53], v[194:197], v[202:205], 0
	v_mfma_f32_16x16x32_bf16 v[42:45], v[186:189], v[210:213], 0
	v_mfma_f32_16x16x32_bf16 v[34:37], v[194:197], v[210:213], 0
	v_mfma_f32_16x16x32_bf16 v[26:29], v[186:189], v[218:221], 0
	v_mfma_f32_16x16x32_bf16 v[18:21], v[194:197], v[218:221], 0
	v_mfma_f32_16x16x32_bf16 v[10:13], v[186:189], v[226:229], 0
	v_mfma_f32_16x16x32_bf16 v[2:5], v[194:197], v[226:229], 0
	v_mfma_f32_16x16x32_bf16 v[58:61], v[190:193], v[206:209], v[58:61]
	v_mfma_f32_16x16x32_bf16 v[50:53], v[198:201], v[206:209], v[50:53]
	v_mfma_f32_16x16x32_bf16 v[42:45], v[190:193], v[214:217], v[42:45]
	v_mfma_f32_16x16x32_bf16 v[34:37], v[198:201], v[214:217], v[34:37]
	v_mfma_f32_16x16x32_bf16 v[26:29], v[190:193], v[222:225], v[26:29]
	v_mfma_f32_16x16x32_bf16 v[18:21], v[198:201], v[222:225], v[18:21]
	v_mfma_f32_16x16x32_bf16 v[10:13], v[190:193], v[230:233], v[10:13]
	v_mfma_f32_16x16x32_bf16 v[2:5], v[198:201], v[230:233], v[2:5]
	s_setprio 0
	s_barrier
	s_add_i32 s66, 0, 0x18000
	v_add_u32_e32 v165, s66, v156
	s_add_i32 s67, 0, 0x1c000
	ds_read_b128 v[166:169], v165
	ds_read_b128 v[170:173], v165 offset:1024
	ds_read_b128 v[174:177], v165 offset:2048
	ds_read_b128 v[178:181], v165 offset:3072
	v_add_u32_e32 v165, s67, v156
	ds_read_b128 v[186:189], v165
	ds_read_b128 v[190:193], v165 offset:1024
	ds_read_b128 v[194:197], v165 offset:2048
	ds_read_b128 v[198:201], v165 offset:3072
	s_add_u32 s44, s44, 0x40000
	s_addc_u32 s45, s45, 0
	s_mov_b32 m0, s51
	v_lshl_add_u64 v[240:241], s[44:45], 0, v[136:137]
	ds_read_b128 v[202:205], v158 offset:32768
	ds_read_b128 v[206:209], v158 offset:33792
	ds_read_b128 v[210:213], v158 offset:34816
	ds_read_b128 v[214:217], v158 offset:35840
	ds_read_b128 v[218:221], v158 offset:36864
	ds_read_b128 v[222:225], v158 offset:37888
	ds_read_b128 v[226:229], v158 offset:38912
	ds_read_b128 v[230:233], v158 offset:39936
	global_load_lds_dwordx4 v[240:241], off
	v_lshl_add_u64 v[240:241], s[44:45], 0, v[132:133]
	s_mov_b32 m0, s52
	s_nop 0
	global_load_lds_dwordx4 v[240:241], off
	s_waitcnt vmcnt(8)
	s_waitcnt lgkmcnt(0)
	s_barrier
	s_setprio 1
	s_waitcnt lgkmcnt(0)
	v_mfma_f32_16x16x32_bf16 v[126:129], v[166:169], v[202:205], v[126:129]
	v_mfma_f32_16x16x32_bf16 v[118:121], v[174:177], v[202:205], v[118:121]
	v_mfma_f32_16x16x32_bf16 v[110:113], v[166:169], v[210:213], v[110:113]
	v_mfma_f32_16x16x32_bf16 v[102:105], v[174:177], v[210:213], v[102:105]
	v_mfma_f32_16x16x32_bf16 v[94:97], v[166:169], v[218:221], v[94:97]
	v_mfma_f32_16x16x32_bf16 v[86:89], v[174:177], v[218:221], v[86:89]
	v_mfma_f32_16x16x32_bf16 v[78:81], v[166:169], v[226:229], v[78:81]
	v_mfma_f32_16x16x32_bf16 v[70:73], v[174:177], v[226:229], v[70:73]
	v_mfma_f32_16x16x32_bf16 v[126:129], v[170:173], v[206:209], v[126:129]
	v_mfma_f32_16x16x32_bf16 v[118:121], v[178:181], v[206:209], v[118:121]
	v_mfma_f32_16x16x32_bf16 v[110:113], v[170:173], v[214:217], v[110:113]
	v_mfma_f32_16x16x32_bf16 v[102:105], v[178:181], v[214:217], v[102:105]
	v_mfma_f32_16x16x32_bf16 v[94:97], v[170:173], v[222:225], v[94:97]
	v_mfma_f32_16x16x32_bf16 v[86:89], v[178:181], v[222:225], v[86:89]
	v_mfma_f32_16x16x32_bf16 v[78:81], v[170:173], v[230:233], v[78:81]
	v_mfma_f32_16x16x32_bf16 v[70:73], v[178:181], v[230:233], v[70:73]
	s_setprio 0
	s_setprio 1
	v_mfma_f32_16x16x32_bf16 v[122:125], v[186:189], v[202:205], v[122:125]
	v_mfma_f32_16x16x32_bf16 v[114:117], v[194:197], v[202:205], v[114:117]
	v_mfma_f32_16x16x32_bf16 v[106:109], v[186:189], v[210:213], v[106:109]
	v_mfma_f32_16x16x32_bf16 v[98:101], v[194:197], v[210:213], v[98:101]
	v_mfma_f32_16x16x32_bf16 v[90:93], v[186:189], v[218:221], v[90:93]
	v_mfma_f32_16x16x32_bf16 v[82:85], v[194:197], v[218:221], v[82:85]
	v_mfma_f32_16x16x32_bf16 v[74:77], v[186:189], v[226:229], v[74:77]
	v_mfma_f32_16x16x32_bf16 v[66:69], v[194:197], v[226:229], v[66:69]
	v_mfma_f32_16x16x32_bf16 v[122:125], v[190:193], v[206:209], v[122:125]
	v_mfma_f32_16x16x32_bf16 v[114:117], v[198:201], v[206:209], v[114:117]
	v_mfma_f32_16x16x32_bf16 v[106:109], v[190:193], v[214:217], v[106:109]
	v_mfma_f32_16x16x32_bf16 v[98:101], v[198:201], v[214:217], v[98:101]
	v_mfma_f32_16x16x32_bf16 v[90:93], v[190:193], v[222:225], v[90:93]
	v_mfma_f32_16x16x32_bf16 v[82:85], v[198:201], v[222:225], v[82:85]
	v_mfma_f32_16x16x32_bf16 v[74:77], v[190:193], v[230:233], v[74:77]
	v_mfma_f32_16x16x32_bf16 v[66:69], v[198:201], v[230:233], v[66:69]
	s_setprio 0
	s_barrier
; #define PG8_STAGE(bufoff, gbase, voff) do { _Pragma("unroll") for (int _i = 0; _i < 2; ++_i) \
;         __builtin_amdgcn_global_load_lds((const unsigned*)((const char*)(gbase) + (voff)[_i]), (LAS unsigned*)(lds + (bufoff) + ldsw + _i * 8192), 16, 0, 0); } while (0)
; #define PG8_LDA(dst, b, h) do { _Pragma("unroll") for (int m = 0; m < 4; ++m) _Pragma("unroll") for (int k = 0; k < 2; ++k) dst[m][k] = *(const LAS bf16x8*)(lds + PG8_SA(b, h) + aoff + m * 2048 + k * 1024); } while (0)
; #define PG8_MMA(ai, bj, At, Bt) do { __builtin_amdgcn_s_setprio(1); _Pragma("unroll") for (int m = 0; m < 4; ++m) _Pragma("unroll") for (int n = 0; n < 2; ++n) _Pragma("unroll") for (int k = 0; k < 2; ++k) \
;         acc[ai][bj][m][n] = __builtin_amdgcn_mfma_f32_16x16x32_bf16(Bt[n][k], At[m][k], acc[ai][bj][m][n], 0, 0, 0); __builtin_amdgcn_s_setprio(0); } while (0)
; #define PG8_WAIT_V(n) asm volatile("s_waitcnt vmcnt(" #n ")" ::: "memory")
; #define PG8_WAIT_L(n) asm volatile("s_waitcnt lgkmcnt(" #n ")" ::: "memory")
; #define PG8_BAR __builtin_amdgcn_s_barrier()
; #define PG8_SCHED __builtin_amdgcn_sched_barrier(0)
; template <class Epi, class Sched>
; DI void gemm_phase(LAS unsigned char* lds, const Gemm g, const Sched& S, const Epi& E) {
;     ...
;             PG8_WAIT_V(8); PG8_WAIT_L(0); PG8_BAR; PG8_MMA(0, 0, At, B0); PG8_MMA(0, 1, At, B1); PG8_BAR; PG8_SCHED;
;             PG8_LDA(At, 1, 1); PG8_STAGE(PG8_SB(1, 0), b3, voffB); PG8_STAGE(PG8_SB(1, 1), b3 + hstepB, voffB); PG8_STAGE(PG8_SA(1, 0), a3, voffA);
;             PG8_WAIT_V(8); PG8_WAIT_L(0); PG8_BAR; PG8_MMA(1, 0, At, B0); PG8_MMA(1, 1, At, B1); PG8_BAR; PG8_SCHED;
;         }
	s_add_i32 s44, s66, s46
	v_lshl_add_u64 v[182:183], v[182:183], 0, s[16:17]
	s_mov_b32 m0, s44
	ds_read_b128 v[202:205], v158 offset:49152
	ds_read_b128 v[206:209], v158 offset:50176
	ds_read_b128 v[210:213], v158 offset:51200
	ds_read_b128 v[214:217], v158 offset:52224
	ds_read_b128 v[218:221], v158 offset:53248
	ds_read_b128 v[222:225], v158 offset:54272
	ds_read_b128 v[226:229], v158 offset:55296
	ds_read_b128 v[230:233], v158 offset:56320
	global_load_lds_dwordx4 v[182:183], off
	s_add_i32 m0, s44, 0x2000
	s_add_u32 s42, s42, 0x40080
	v_lshl_add_u64 v[182:183], v[234:235], 0, s[16:17]
	s_addc_u32 s43, s43, 0
	s_add_i32 s44, s67, s46
	global_load_lds_dwordx4 v[182:183], off
	v_lshl_add_u64 v[182:183], s[42:43], 0, v[134:135]
	s_mov_b32 m0, s44
	s_nop 0
	global_load_lds_dwordx4 v[182:183], off
	v_lshl_add_u64 v[182:183], s[42:43], 0, v[130:131]
	s_add_i32 m0, s44, 0x2000
	s_nop 0
	global_load_lds_dwordx4 v[182:183], off
	v_lshl_add_u64 v[182:183], v[236:237], 0, s[16:17]
	s_mov_b32 m0, s54
	s_nop 0
	global_load_lds_dwordx4 v[182:183], off
	v_lshl_add_u64 v[182:183], v[238:239], 0, s[16:17]
	s_mov_b32 m0, s55
	s_nop 0
	global_load_lds_dwordx4 v[182:183], off
	s_waitcnt vmcnt(8)
	s_waitcnt lgkmcnt(0)
	s_barrier
	s_setprio 1
	s_waitcnt lgkmcnt(0)
	v_mfma_f32_16x16x32_bf16 v[62:65], v[166:169], v[202:205], v[62:65]
	v_mfma_f32_16x16x32_bf16 v[54:57], v[174:177], v[202:205], v[54:57]
	v_mfma_f32_16x16x32_bf16 v[46:49], v[166:169], v[210:213], v[46:49]
	v_mfma_f32_16x16x32_bf16 v[38:41], v[174:177], v[210:213], v[38:41]
	v_mfma_f32_16x16x32_bf16 v[30:33], v[166:169], v[218:221], v[30:33]
	v_mfma_f32_16x16x32_bf16 v[22:25], v[174:177], v[218:221], v[22:25]
	v_mfma_f32_16x16x32_bf16 v[14:17], v[166:169], v[226:229], v[14:17]
	v_mfma_f32_16x16x32_bf16 v[6:9], v[174:177], v[226:229], v[6:9]
	v_mfma_f32_16x16x32_bf16 v[62:65], v[170:173], v[206:209], v[62:65]
	v_mfma_f32_16x16x32_bf16 v[54:57], v[178:181], v[206:209], v[54:57]
	v_mfma_f32_16x16x32_bf16 v[46:49], v[170:173], v[214:217], v[46:49]
	v_mfma_f32_16x16x32_bf16 v[38:41], v[178:181], v[214:217], v[38:41]
	v_mfma_f32_16x16x32_bf16 v[30:33], v[170:173], v[222:225], v[30:33]
	v_mfma_f32_16x16x32_bf16 v[22:25], v[178:181], v[222:225], v[22:25]
	v_mfma_f32_16x16x32_bf16 v[14:17], v[170:173], v[230:233], v[14:17]
	v_mfma_f32_16x16x32_bf16 v[6:9], v[178:181], v[230:233], v[6:9]
	s_setprio 0
	s_setprio 1
	v_mfma_f32_16x16x32_bf16 v[58:61], v[186:189], v[202:205], v[58:61]
	v_mfma_f32_16x16x32_bf16 v[50:53], v[194:197], v[202:205], v[50:53]
	v_mfma_f32_16x16x32_bf16 v[42:45], v[186:189], v[210:213], v[42:45]
	v_mfma_f32_16x16x32_bf16 v[34:37], v[194:197], v[210:213], v[34:37]
	v_mfma_f32_16x16x32_bf16 v[26:29], v[186:189], v[218:221], v[26:29]
	v_mfma_f32_16x16x32_bf16 v[18:21], v[194:197], v[218:221], v[18:21]
	v_mfma_f32_16x16x32_bf16 v[10:13], v[186:189], v[226:229], v[10:13]
	v_mfma_f32_16x16x32_bf16 v[2:5], v[194:197], v[226:229], v[2:5]
	v_mfma_f32_16x16x32_bf16 v[58:61], v[190:193], v[206:209], v[58:61]
	v_mfma_f32_16x16x32_bf16 v[50:53], v[198:201], v[206:209], v[50:53]
	v_mfma_f32_16x16x32_bf16 v[42:45], v[190:193], v[214:217], v[42:45]
	v_mfma_f32_16x16x32_bf16 v[34:37], v[198:201], v[214:217], v[34:37]
	v_mfma_f32_16x16x32_bf16 v[26:29], v[190:193], v[222:225], v[26:29]
	v_mfma_f32_16x16x32_bf16 v[18:21], v[198:201], v[222:225], v[18:21]
	v_mfma_f32_16x16x32_bf16 v[10:13], v[190:193], v[230:233], v[10:13]
	v_mfma_f32_16x16x32_bf16 v[2:5], v[198:201], v[230:233], v[2:5]
	s_setprio 0
	s_barrier
	s_add_i32 s65, s65, 2
	s_add_u32 s40, s40, 0x100
	s_addc_u32 s41, s41, 0
	s_add_u32 s63, s63, 0x100
	s_addc_u32 s64, s64, 0
	s_cmp_gt_u32 s65, 13

; #define PG8_STAGE(bufoff, gbase, voff) do { _Pragma("unroll") for (int _i = 0; _i < 2; ++_i) \
;         __builtin_amdgcn_global_load_lds((const unsigned*)((const char*)(gbase) + (voff)[_i]), (LAS unsigned*)(lds + (bufoff) + ldsw + _i * 8192), 16, 0, 0); } while (0)
; #define PG8_LDA(dst, b, h) do { _Pragma("unroll") for (int m = 0; m < 4; ++m) _Pragma("unroll") for (int k = 0; k < 2; ++k) dst[m][k] = *(const LAS bf16x8*)(lds + PG8_SA(b, h) + aoff + m * 2048 + k * 1024); } while (0)
; #define PG8_LDB(dst, b, h) do { _Pragma("unroll") for (int n = 0; n < 2; ++n) _Pragma("unroll") for (int k = 0; k < 2; ++k) dst[n][k] = *(const LAS bf16x8*)(lds + PG8_SB(b, h) + boff + n * 2048 + k * 1024); } while (0)
; #define PG8_MMA(ai, bj, At, Bt) do { __builtin_amdgcn_s_setprio(1); _Pragma("unroll") for (int m = 0; m < 4; ++m) _Pragma("unroll") for (int n = 0; n < 2; ++n) _Pragma("unroll") for (int k = 0; k < 2; ++k) \
;         acc[ai][bj][m][n] = __builtin_amdgcn_mfma_f32_16x16x32_bf16(Bt[n][k], At[m][k], acc[ai][bj][m][n], 0, 0, 0); __builtin_amdgcn_s_setprio(0); } while (0)
; #define PG8_WAIT_V(n) asm volatile("s_waitcnt vmcnt(" #n ")" ::: "memory")
; template <class Epi, class Sched>
; DI void gemm_phase(LAS unsigned char* lds, const Gemm g, const Sched& S, const Epi& E) {
;     ...
;         const char* nA = has_next ? (const char*)(nxt.src ? g.A1 : g.A0) + (size_t)nxt.pm * tstepA : cA; const char* nB = has_next ? (const char*)(nxt.src ? g.B1 : g.B0) + (size_t)nxt.pn * tstepB : cB;
;         for (int t = 0; t < nt; t += 2) {
;             const bool last = (t == nt - 2);
;             const char* a1 = cA + (size_t)(t + 1) * kstep;
;             const char* a2 = last ? nA : cA + (size_t)(t + 2) * kstep; const char* b2 = last ? nB : cB + (size_t)(t + 2) * kstep;
;             const char* a3 = a2 + kstep; const char* b3 = b2 + kstep;
;             PG8_LDB(B0, 0, 0); PG8_LDB(B1, 0, 1); PG8_SCHED; PG8_LDA(At, 0, 0); PG8_STAGE(PG8_SA(1, 1), a1 + hstepA, voffA);
;             PG8_WAIT_V(8); PG8_WAIT_L(0); PG8_BAR; PG8_MMA(0, 0, At, B0); PG8_MMA(0, 1, At, B1); PG8_BAR; PG8_SCHED;
;             PG8_LDA(At, 0, 1); PG8_STAGE(PG8_SB(0, 0), b2, voffB); PG8_STAGE(PG8_SB(0, 1), b2 + hstepB, voffB); PG8_STAGE(PG8_SA(0, 0), a2, voffA);
;             PG8_WAIT_V(8); PG8_WAIT_L(0); PG8_BAR; PG8_MMA(1, 0, At, B0); PG8_MMA(1, 1, At, B1); PG8_BAR; PG8_SCHED;
.LBB0_1330:
	s_add_u32 s16, s16, 0xb0080
	s_addc_u32 s17, s17, 0
	s_add_u32 s45, s18, 0x100
	s_addc_u32 s46, s19, 0
	s_mov_b32 s47, -2
	s_waitcnt vmcnt(0)
	ds_read_b128 v[144:147], v151
	ds_read_b128 v[154:157], v151 offset:1024
	ds_read_b128 v[158:161], v151 offset:2048
	ds_read_b128 v[162:165], v151 offset:3072
	ds_read_b128 v[166:169], v152
	ds_read_b128 v[170:173], v152 offset:1024
	ds_read_b128 v[174:177], v152 offset:2048
	ds_read_b128 v[178:181], v152 offset:3072
	s_add_u32 s18, s16, 0xfff50080
	s_addc_u32 s19, s17, -1
	s_cmp_eq_u32 s47, 40
	s_cselect_b32 s21, s5, s19
	s_cselect_b32 s20, s4, s18
	s_cselect_b32 s19, s15, s46
	s_cselect_b32 s18, s14, s45
	v_lshl_add_u64 v[214:215], s[16:17], 0, v[136:137]
	s_add_i32 m0, s28, 0xc000
	ds_read_b128 v[182:185], v153
	ds_read_b128 v[186:189], v153 offset:1024
	ds_read_b128 v[190:193], v153 offset:2048
	ds_read_b128 v[194:197], v153 offset:3072
	ds_read_b128 v[198:201], v153 offset:4096
	ds_read_b128 v[202:205], v153 offset:5120
	ds_read_b128 v[206:209], v153 offset:6144
	ds_read_b128 v[210:213], v153 offset:7168
	global_load_lds_dwordx4 v[214:215], off
	v_lshl_add_u64 v[214:215], s[16:17], 0, v[138:139]
	s_add_i32 m0, s28, 0xe000
	s_nop 0
	global_load_lds_dwordx4 v[214:215], off
	s_waitcnt vmcnt(8)
	s_waitcnt lgkmcnt(0)
	s_barrier
	s_setprio 1
	s_waitcnt lgkmcnt(0)
	v_mfma_f32_16x16x32_bf16 v[124:127], v[144:147], v[182:185], 0
	v_mfma_f32_16x16x32_bf16 v[120:123], v[158:161], v[182:185], 0
	v_mfma_f32_16x16x32_bf16 v[108:111], v[144:147], v[190:193], 0
	v_mfma_f32_16x16x32_bf16 v[104:107], v[158:161], v[190:193], 0
	v_mfma_f32_16x16x32_bf16 v[92:95], v[144:147], v[198:201], 0
	v_mfma_f32_16x16x32_bf16 v[88:91], v[158:161], v[198:201], 0
	v_mfma_f32_16x16x32_bf16 v[76:79], v[144:147], v[206:209], 0
	v_mfma_f32_16x16x32_bf16 v[72:75], v[158:161], v[206:209], 0
	v_mfma_f32_16x16x32_bf16 v[124:127], v[154:157], v[186:189], v[124:127]
	v_mfma_f32_16x16x32_bf16 v[120:123], v[162:165], v[186:189], v[120:123]
	v_mfma_f32_16x16x32_bf16 v[108:111], v[154:157], v[194:197], v[108:111]
	v_mfma_f32_16x16x32_bf16 v[104:107], v[162:165], v[194:197], v[104:107]
	v_mfma_f32_16x16x32_bf16 v[92:95], v[154:157], v[202:205], v[92:95]
	v_mfma_f32_16x16x32_bf16 v[88:91], v[162:165], v[202:205], v[88:91]
	v_mfma_f32_16x16x32_bf16 v[76:79], v[154:157], v[210:213], v[76:79]
	v_mfma_f32_16x16x32_bf16 v[72:75], v[162:165], v[210:213], v[72:75]
	s_setprio 0
	s_setprio 1
	v_mfma_f32_16x16x32_bf16 v[116:119], v[166:169], v[182:185], 0
	v_mfma_f32_16x16x32_bf16 v[112:115], v[174:177], v[182:185], 0
	v_mfma_f32_16x16x32_bf16 v[100:103], v[166:169], v[190:193], 0
	v_mfma_f32_16x16x32_bf16 v[96:99], v[174:177], v[190:193], 0
	v_mfma_f32_16x16x32_bf16 v[84:87], v[166:169], v[198:201], 0
	v_mfma_f32_16x16x32_bf16 v[80:83], v[174:177], v[198:201], 0
	v_mfma_f32_16x16x32_bf16 v[68:71], v[166:169], v[206:209], 0
	v_mfma_f32_16x16x32_bf16 v[64:67], v[174:177], v[206:209], 0
	v_mfma_f32_16x16x32_bf16 v[116:119], v[170:173], v[186:189], v[116:119]
	v_mfma_f32_16x16x32_bf16 v[112:115], v[178:181], v[186:189], v[112:115]
	v_mfma_f32_16x16x32_bf16 v[100:103], v[170:173], v[194:197], v[100:103]
	v_mfma_f32_16x16x32_bf16 v[96:99], v[178:181], v[194:197], v[96:99]
	v_mfma_f32_16x16x32_bf16 v[84:87], v[170:173], v[202:205], v[84:87]
	v_mfma_f32_16x16x32_bf16 v[80:83], v[178:181], v[202:205], v[80:83]
	v_mfma_f32_16x16x32_bf16 v[68:71], v[170:173], v[210:213], v[68:71]
	v_mfma_f32_16x16x32_bf16 v[64:67], v[178:181], v[210:213], v[64:67]
	s_setprio 0
	s_barrier
	s_add_i32 s48, s39, s27
	v_lshl_add_u64 v[214:215], s[18:19], 0, v[130:131]
	s_mov_b32 m0, s48
	ds_read_b128 v[182:185], v153 offset:16384
	ds_read_b128 v[186:189], v153 offset:17408
	ds_read_b128 v[190:193], v153 offset:18432
	ds_read_b128 v[194:197], v153 offset:19456
	ds_read_b128 v[198:201], v153 offset:20480
	ds_read_b128 v[202:205], v153 offset:21504
	ds_read_b128 v[206:209], v153 offset:22528
	ds_read_b128 v[210:213], v153 offset:23552
	global_load_lds_dwordx4 v[214:215], off
	s_add_i32 m0, s48, 0x2000
	s_add_u32 s48, s18, 0xb0000
	v_lshl_add_u64 v[216:217], s[18:19], 0, v[134:135]
	s_addc_u32 s49, s19, 0
	s_add_i32 s50, s40, s27
	global_load_lds_dwordx4 v[216:217], off
	v_lshl_add_u64 v[218:219], s[48:49], 0, v[130:131]
	s_mov_b32 m0, s50
	v_lshl_add_u64 v[220:221], s[20:21], 0, v[132:133]
	global_load_lds_dwordx4 v[218:219], off
	v_lshl_add_u64 v[218:219], s[48:49], 0, v[134:135]
	s_add_i32 m0, s50, 0x2000
	s_nop 0
	global_load_lds_dwordx4 v[218:219], off
	v_lshl_add_u64 v[218:219], s[20:21], 0, v[128:129]
	s_mov_b32 m0, s28
	s_nop 0
	global_load_lds_dwordx4 v[218:219], off
	s_mov_b32 m0, s29
	s_nop 0
	global_load_lds_dwordx4 v[220:221], off
	s_waitcnt vmcnt(8)
	s_waitcnt lgkmcnt(0)
	s_barrier
; #define PG8_STAGE(bufoff, gbase, voff) do { _Pragma("unroll") for (int _i = 0; _i < 2; ++_i) \
;         __builtin_amdgcn_global_load_lds((const unsigned*)((const char*)(gbase) + (voff)[_i]), (LAS unsigned*)(lds + (bufoff) + ldsw + _i * 8192), 16, 0, 0); } while (0)
; #define PG8_LDA(dst, b, h) do { _Pragma("unroll") for (int m = 0; m < 4; ++m) _Pragma("unroll") for (int k = 0; k < 2; ++k) dst[m][k] = *(const LAS bf16x8*)(lds + PG8_SA(b, h) + aoff + m * 2048 + k * 1024); } while (0)
; #define PG8_LDB(dst, b, h) do { _Pragma("unroll") for (int n = 0; n < 2; ++n) _Pragma("unroll") for (int k = 0; k < 2; ++k) dst[n][k] = *(const LAS bf16x8*)(lds + PG8_SB(b, h) + boff + n * 2048 + k * 1024); } while (0)
; #define PG8_MMA(ai, bj, At, Bt) do { __builtin_amdgcn_s_setprio(1); _Pragma("unroll") for (int m = 0; m < 4; ++m) _Pragma("unroll") for (int n = 0; n < 2; ++n) _Pragma("unroll") for (int k = 0; k < 2; ++k) \
;         acc[ai][bj][m][n] = __builtin_amdgcn_mfma_f32_16x16x32_bf16(Bt[n][k], At[m][k], acc[ai][bj][m][n], 0, 0, 0); __builtin_amdgcn_s_setprio(0); } while (0)
; #define PG8_WAIT_V(n) asm volatile("s_waitcnt vmcnt(" #n ")" ::: "memory")
; #define PG8_WAIT_L(n) asm volatile("s_waitcnt lgkmcnt(" #n ")" ::: "memory")
; #define PG8_BAR __builtin_amdgcn_s_barrier()
; #define PG8_SCHED __builtin_amdgcn_sched_barrier(0)
; template <class Epi, class Sched>
; DI void gemm_phase(LAS unsigned char* lds, const Gemm g, const Sched& S, const Epi& E) {
;     ...
;             PG8_WAIT_V(8); PG8_WAIT_L(0); PG8_BAR; PG8_MMA(0, 0, At, B0); PG8_MMA(0, 1, At, B1); PG8_BAR; PG8_SCHED;
;             PG8_LDA(At, 0, 1); PG8_STAGE(PG8_SB(0, 0), b2, voffB); PG8_STAGE(PG8_SB(0, 1), b2 + hstepB, voffB); PG8_STAGE(PG8_SA(0, 0), a2, voffA);
;             PG8_WAIT_V(8); PG8_WAIT_L(0); PG8_BAR; PG8_MMA(1, 0, At, B0); PG8_MMA(1, 1, At, B1); PG8_BAR; PG8_SCHED;
;             PG8_LDB(B0, 1, 0); PG8_LDB(B1, 1, 1); PG8_SCHED; PG8_LDA(At, 1, 0); PG8_STAGE(PG8_SA(0, 1), a2 + hstepA, voffA);
;             PG8_WAIT_V(8); PG8_WAIT_L(0); PG8_BAR; PG8_MMA(0, 0, At, B0); PG8_MMA(0, 1, At, B1); PG8_BAR; PG8_SCHED;
	s_setprio 1
	s_waitcnt lgkmcnt(0)
	v_mfma_f32_16x16x32_bf16 v[60:63], v[144:147], v[182:185], 0
	v_mfma_f32_16x16x32_bf16 v[56:59], v[158:161], v[182:185], 0
	v_mfma_f32_16x16x32_bf16 v[44:47], v[144:147], v[190:193], 0
	v_mfma_f32_16x16x32_bf16 v[40:43], v[158:161], v[190:193], 0
	v_mfma_f32_16x16x32_bf16 v[28:31], v[144:147], v[198:201], 0
	v_mfma_f32_16x16x32_bf16 v[24:27], v[158:161], v[198:201], 0
	v_mfma_f32_16x16x32_bf16 v[12:15], v[144:147], v[206:209], 0
	v_mfma_f32_16x16x32_bf16 v[8:11], v[158:161], v[206:209], 0
	v_mfma_f32_16x16x32_bf16 v[60:63], v[154:157], v[186:189], v[60:63]
	v_mfma_f32_16x16x32_bf16 v[56:59], v[162:165], v[186:189], v[56:59]
	v_mfma_f32_16x16x32_bf16 v[44:47], v[154:157], v[194:197], v[44:47]
	v_mfma_f32_16x16x32_bf16 v[40:43], v[162:165], v[194:197], v[40:43]
	v_mfma_f32_16x16x32_bf16 v[28:31], v[154:157], v[202:205], v[28:31]
	v_mfma_f32_16x16x32_bf16 v[24:27], v[162:165], v[202:205], v[24:27]
	v_mfma_f32_16x16x32_bf16 v[12:15], v[154:157], v[210:213], v[12:15]
	v_mfma_f32_16x16x32_bf16 v[8:11], v[162:165], v[210:213], v[8:11]
	s_setprio 0
	s_setprio 1
	v_mfma_f32_16x16x32_bf16 v[52:55], v[166:169], v[182:185], 0
	v_mfma_f32_16x16x32_bf16 v[48:51], v[174:177], v[182:185], 0
	v_mfma_f32_16x16x32_bf16 v[36:39], v[166:169], v[190:193], 0
	v_mfma_f32_16x16x32_bf16 v[32:35], v[174:177], v[190:193], 0
	v_mfma_f32_16x16x32_bf16 v[20:23], v[166:169], v[198:201], 0
	v_mfma_f32_16x16x32_bf16 v[16:19], v[174:177], v[198:201], 0
	v_mfma_f32_16x16x32_bf16 v[4:7], v[166:169], v[206:209], 0
	v_mfma_f32_16x16x32_bf16 v[0:3], v[174:177], v[206:209], 0
	v_mfma_f32_16x16x32_bf16 v[52:55], v[170:173], v[186:189], v[52:55]
	v_mfma_f32_16x16x32_bf16 v[48:51], v[178:181], v[186:189], v[48:51]
	v_mfma_f32_16x16x32_bf16 v[36:39], v[170:173], v[194:197], v[36:39]
	v_mfma_f32_16x16x32_bf16 v[32:35], v[178:181], v[194:197], v[32:35]
	v_mfma_f32_16x16x32_bf16 v[20:23], v[170:173], v[202:205], v[20:23]
	v_mfma_f32_16x16x32_bf16 v[16:19], v[178:181], v[202:205], v[16:19]
	v_mfma_f32_16x16x32_bf16 v[4:7], v[170:173], v[210:213], v[4:7]
	v_mfma_f32_16x16x32_bf16 v[0:3], v[178:181], v[210:213], v[0:3]
	s_setprio 0
	s_barrier
	s_add_i32 s48, 0, 0x18000
	s_add_i32 s49, 0, 0x1c000
	v_add_u32_e32 v162, s48, v149
	v_add_u32_e32 v178, s49, v149
	ds_read_b128 v[144:147], v162
	ds_read_b128 v[154:157], v162 offset:1024
	ds_read_b128 v[158:161], v162 offset:2048
	ds_read_b128 v[162:165], v162 offset:3072
	ds_read_b128 v[166:169], v178
	ds_read_b128 v[170:173], v178 offset:1024
	ds_read_b128 v[174:177], v178 offset:2048
	ds_read_b128 v[178:181], v178 offset:3072
	s_add_u32 s20, s20, 0xb0000
	s_addc_u32 s21, s21, 0
	s_mov_b32 m0, s33
	v_lshl_add_u64 v[222:223], s[20:21], 0, v[128:129]
	ds_read_b128 v[182:185], v153 offset:32768
	ds_read_b128 v[186:189], v153 offset:33792
	ds_read_b128 v[190:193], v153 offset:34816
	ds_read_b128 v[194:197], v153 offset:35840
	ds_read_b128 v[198:201], v153 offset:36864
	ds_read_b128 v[202:205], v153 offset:37888
	ds_read_b128 v[206:209], v153 offset:38912
	ds_read_b128 v[210:213], v153 offset:39936
	global_load_lds_dwordx4 v[222:223], off
	v_lshl_add_u64 v[222:223], s[20:21], 0, v[132:133]
	s_mov_b32 m0, s34
	s_nop 0
	global_load_lds_dwordx4 v[222:223], off
	s_waitcnt vmcnt(8)
	s_waitcnt lgkmcnt(0)
	s_barrier
	s_setprio 1
	s_waitcnt lgkmcnt(0)
	v_mfma_f32_16x16x32_bf16 v[124:127], v[144:147], v[182:185], v[124:127]
	v_mfma_f32_16x16x32_bf16 v[120:123], v[158:161], v[182:185], v[120:123]
	v_mfma_f32_16x16x32_bf16 v[108:111], v[144:147], v[190:193], v[108:111]
	v_mfma_f32_16x16x32_bf16 v[104:107], v[158:161], v[190:193], v[104:107]
	v_mfma_f32_16x16x32_bf16 v[92:95], v[144:147], v[198:201], v[92:95]
	v_mfma_f32_16x16x32_bf16 v[88:91], v[158:161], v[198:201], v[88:91]
	v_mfma_f32_16x16x32_bf16 v[76:79], v[144:147], v[206:209], v[76:79]
	v_mfma_f32_16x16x32_bf16 v[72:75], v[158:161], v[206:209], v[72:75]
	v_mfma_f32_16x16x32_bf16 v[124:127], v[154:157], v[186:189], v[124:127]
	v_mfma_f32_16x16x32_bf16 v[120:123], v[162:165], v[186:189], v[120:123]
	v_mfma_f32_16x16x32_bf16 v[108:111], v[154:157], v[194:197], v[108:111]
	v_mfma_f32_16x16x32_bf16 v[104:107], v[162:165], v[194:197], v[104:107]
	v_mfma_f32_16x16x32_bf16 v[92:95], v[154:157], v[202:205], v[92:95]
	v_mfma_f32_16x16x32_bf16 v[88:91], v[162:165], v[202:205], v[88:91]
	v_mfma_f32_16x16x32_bf16 v[76:79], v[154:157], v[210:213], v[76:79]
	v_mfma_f32_16x16x32_bf16 v[72:75], v[162:165], v[210:213], v[72:75]
	s_setprio 0
	s_setprio 1
	v_mfma_f32_16x16x32_bf16 v[116:119], v[166:169], v[182:185], v[116:119]
	v_mfma_f32_16x16x32_bf16 v[112:115], v[174:177], v[182:185], v[112:115]
	v_mfma_f32_16x16x32_bf16 v[100:103], v[166:169], v[190:193], v[100:103]
	v_mfma_f32_16x16x32_bf16 v[96:99], v[174:177], v[190:193], v[96:99]
	v_mfma_f32_16x16x32_bf16 v[84:87], v[166:169], v[198:201], v[84:87]
	v_mfma_f32_16x16x32_bf16 v[80:83], v[174:177], v[198:201], v[80:83]
	v_mfma_f32_16x16x32_bf16 v[68:71], v[166:169], v[206:209], v[68:71]
	v_mfma_f32_16x16x32_bf16 v[64:67], v[174:177], v[206:209], v[64:67]
	v_mfma_f32_16x16x32_bf16 v[116:119], v[170:173], v[186:189], v[116:119]
	v_mfma_f32_16x16x32_bf16 v[112:115], v[178:181], v[186:189], v[112:115]
	v_mfma_f32_16x16x32_bf16 v[100:103], v[170:173], v[194:197], v[100:103]
	v_mfma_f32_16x16x32_bf16 v[96:99], v[178:181], v[194:197], v[96:99]
	v_mfma_f32_16x16x32_bf16 v[84:87], v[170:173], v[202:205], v[84:87]
	v_mfma_f32_16x16x32_bf16 v[80:83], v[178:181], v[202:205], v[80:83]
	v_mfma_f32_16x16x32_bf16 v[68:71], v[170:173], v[210:213], v[68:71]
	v_mfma_f32_16x16x32_bf16 v[64:67], v[178:181], v[210:213], v[64:67]
	s_setprio 0
	s_barrier
; #define PG8_STAGE(bufoff, gbase, voff) do { _Pragma("unroll") for (int _i = 0; _i < 2; ++_i) \
;         __builtin_amdgcn_global_load_lds((const unsigned*)((const char*)(gbase) + (voff)[_i]), (LAS unsigned*)(lds + (bufoff) + ldsw + _i * 8192), 16, 0, 0); } while (0)
; #define PG8_LDA(dst, b, h) do { _Pragma("unroll") for (int m = 0; m < 4; ++m) _Pragma("unroll") for (int k = 0; k < 2; ++k) dst[m][k] = *(const LAS bf16x8*)(lds + PG8_SA(b, h) + aoff + m * 2048 + k * 1024); } while (0)
; #define PG8_MMA(ai, bj, At, Bt) do { __builtin_amdgcn_s_setprio(1); _Pragma("unroll") for (int m = 0; m < 4; ++m) _Pragma("unroll") for (int n = 0; n < 2; ++n) _Pragma("unroll") for (int k = 0; k < 2; ++k) \
;         acc[ai][bj][m][n] = __builtin_amdgcn_mfma_f32_16x16x32_bf16(Bt[n][k], At[m][k], acc[ai][bj][m][n], 0, 0, 0); __builtin_amdgcn_s_setprio(0); } while (0)
; #define PG8_WAIT_V(n) asm volatile("s_waitcnt vmcnt(" #n ")" ::: "memory")
; #define PG8_WAIT_L(n) asm volatile("s_waitcnt lgkmcnt(" #n ")" ::: "memory")
; #define PG8_BAR __builtin_amdgcn_s_barrier()
; #define PG8_SCHED __builtin_amdgcn_sched_barrier(0)
; template <class Epi, class Sched>
; DI void gemm_phase(LAS unsigned char* lds, const Gemm g, const Sched& S, const Epi& E) {
;     ...
;         for (int t = 0; t < nt; t += 2) {
;             const bool last = (t == nt - 2);
;             const char* a1 = cA + (size_t)(t + 1) * kstep;
;             const char* a2 = last ? nA : cA + (size_t)(t + 2) * kstep; const char* b2 = last ? nB : cB + (size_t)(t + 2) * kstep;
;     ...
;             PG8_LDA(At, 1, 1); PG8_STAGE(PG8_SB(1, 0), b3, voffB); PG8_STAGE(PG8_SB(1, 1), b3 + hstepB, voffB); PG8_STAGE(PG8_SA(1, 0), a3, voffA);
;             PG8_WAIT_V(8); PG8_WAIT_L(0); PG8_BAR; PG8_MMA(1, 0, At, B0); PG8_MMA(1, 1, At, B1); PG8_BAR; PG8_SCHED;
	s_add_i32 s20, s48, s27
	v_lshl_add_u64 v[214:215], v[214:215], 0, s[10:11]
	s_mov_b32 m0, s20
	ds_read_b128 v[182:185], v153 offset:49152
	ds_read_b128 v[186:189], v153 offset:50176
	ds_read_b128 v[190:193], v153 offset:51200
	ds_read_b128 v[194:197], v153 offset:52224
	ds_read_b128 v[198:201], v153 offset:53248
	ds_read_b128 v[202:205], v153 offset:54272
	ds_read_b128 v[206:209], v153 offset:55296
	ds_read_b128 v[210:213], v153 offset:56320
	global_load_lds_dwordx4 v[214:215], off
	s_add_i32 m0, s20, 0x2000
	s_add_u32 s18, s18, 0xb0080
	v_lshl_add_u64 v[214:215], v[216:217], 0, s[10:11]
	s_addc_u32 s19, s19, 0
	s_add_i32 s20, s49, s27
	global_load_lds_dwordx4 v[214:215], off
	v_lshl_add_u64 v[214:215], s[18:19], 0, v[130:131]
	s_mov_b32 m0, s20
	s_nop 0
	global_load_lds_dwordx4 v[214:215], off
	v_lshl_add_u64 v[214:215], s[18:19], 0, v[134:135]
	s_add_i32 m0, s20, 0x2000
	s_nop 0
	global_load_lds_dwordx4 v[214:215], off
	v_lshl_add_u64 v[214:215], v[218:219], 0, s[10:11]
	s_mov_b32 m0, s36
	s_nop 0
	global_load_lds_dwordx4 v[214:215], off
	v_lshl_add_u64 v[214:215], v[220:221], 0, s[10:11]
	s_mov_b32 m0, s37
	s_nop 0
	global_load_lds_dwordx4 v[214:215], off
	s_waitcnt vmcnt(8)
	s_waitcnt lgkmcnt(0)
	s_barrier
	s_setprio 1
	s_waitcnt lgkmcnt(0)
	v_mfma_f32_16x16x32_bf16 v[60:63], v[144:147], v[182:185], v[60:63]
	v_mfma_f32_16x16x32_bf16 v[56:59], v[158:161], v[182:185], v[56:59]
	v_mfma_f32_16x16x32_bf16 v[44:47], v[144:147], v[190:193], v[44:47]
	v_mfma_f32_16x16x32_bf16 v[40:43], v[158:161], v[190:193], v[40:43]
	v_mfma_f32_16x16x32_bf16 v[28:31], v[144:147], v[198:201], v[28:31]
	v_mfma_f32_16x16x32_bf16 v[24:27], v[158:161], v[198:201], v[24:27]
	v_mfma_f32_16x16x32_bf16 v[12:15], v[144:147], v[206:209], v[12:15]
	v_mfma_f32_16x16x32_bf16 v[8:11], v[158:161], v[206:209], v[8:11]
	v_mfma_f32_16x16x32_bf16 v[60:63], v[154:157], v[186:189], v[60:63]
	v_mfma_f32_16x16x32_bf16 v[56:59], v[162:165], v[186:189], v[56:59]
	v_mfma_f32_16x16x32_bf16 v[44:47], v[154:157], v[194:197], v[44:47]
	v_mfma_f32_16x16x32_bf16 v[40:43], v[162:165], v[194:197], v[40:43]
	v_mfma_f32_16x16x32_bf16 v[28:31], v[154:157], v[202:205], v[28:31]
	v_mfma_f32_16x16x32_bf16 v[24:27], v[162:165], v[202:205], v[24:27]
	v_mfma_f32_16x16x32_bf16 v[12:15], v[154:157], v[210:213], v[12:15]
	v_mfma_f32_16x16x32_bf16 v[8:11], v[162:165], v[210:213], v[8:11]
	s_setprio 0
	s_setprio 1
	v_mfma_f32_16x16x32_bf16 v[52:55], v[166:169], v[182:185], v[52:55]
	v_mfma_f32_16x16x32_bf16 v[48:51], v[174:177], v[182:185], v[48:51]
	v_mfma_f32_16x16x32_bf16 v[36:39], v[166:169], v[190:193], v[36:39]
	v_mfma_f32_16x16x32_bf16 v[32:35], v[174:177], v[190:193], v[32:35]
	v_mfma_f32_16x16x32_bf16 v[20:23], v[166:169], v[198:201], v[20:23]
	v_mfma_f32_16x16x32_bf16 v[16:19], v[174:177], v[198:201], v[16:19]
	v_mfma_f32_16x16x32_bf16 v[4:7], v[166:169], v[206:209], v[4:7]
	v_mfma_f32_16x16x32_bf16 v[0:3], v[174:177], v[206:209], v[0:3]
	v_mfma_f32_16x16x32_bf16 v[52:55], v[170:173], v[186:189], v[52:55]
	v_mfma_f32_16x16x32_bf16 v[48:51], v[178:181], v[186:189], v[48:51]
	v_mfma_f32_16x16x32_bf16 v[36:39], v[170:173], v[194:197], v[36:39]
	v_mfma_f32_16x16x32_bf16 v[32:35], v[178:181], v[194:197], v[32:35]
	v_mfma_f32_16x16x32_bf16 v[20:23], v[170:173], v[202:205], v[20:23]
	v_mfma_f32_16x16x32_bf16 v[16:19], v[178:181], v[202:205], v[16:19]
	v_mfma_f32_16x16x32_bf16 v[4:7], v[170:173], v[210:213], v[4:7]
	v_mfma_f32_16x16x32_bf16 v[0:3], v[178:181], v[210:213], v[0:3]
	s_setprio 0
	s_barrier
	s_add_i32 s47, s47, 2
	s_add_u32 s16, s16, 0x100
	s_addc_u32 s17, s17, 0
	s_add_u32 s45, s45, 0x100
	s_addc_u32 s46, s46, 0
	s_cmp_gt_u32 s47, 41
